# v117 + K-loop counter/exit-test SALU moved into the MFMA shadow of the last segment (one per MFMA gap), only the branch after the barrier
# speedup vs baseline: 1.0121x; 1.0121x over previous
.LBB0_132:
	s_add_u32 s36, s34, 0xfff00080
	s_addc_u32 s37, s35, -1
	s_add_i32 s68, 0, 0x10000
	s_cmp_eq_u32 s67, 60
	s_cselect_b32 s41, s25, s37
	s_cselect_b32 s40, s61, s36
	v_add_u32_e32 v144, s68, v147
	s_cselect_b32 s37, s23, s66
	s_cselect_b32 s36, s62, s63
	s_add_i32 s70, 0, 0x14000
	s_waitcnt lgkmcnt(0)
	ds_read_b128 v[152:155], v144
	ds_read_b128 v[156:159], v144 offset:1024
	ds_read_b128 v[160:163], v144 offset:2048
	ds_read_b128 v[164:167], v144 offset:3072
	v_add_u32_e32 v144, s70, v147
	ds_read_b128 v[168:171], v144
	ds_read_b128 v[172:175], v144 offset:1024
	ds_read_b128 v[176:179], v144 offset:2048
	ds_read_b128 v[180:183], v144 offset:3072
	v_lshl_add_u64 v[212:213], s[34:35], 0, v[140:141]
	s_add_i32 m0, s51, 0xc000
	ds_read_b128 v[184:187], v151
	ds_read_b128 v[188:191], v151 offset:1024
	ds_read_b128 v[192:195], v151 offset:2048
	ds_read_b128 v[196:199], v151 offset:3072
	ds_read_b128 v[200:203], v151 offset:4096
	ds_read_b128 v[204:207], v151 offset:5120
	ds_read_b128 v[208:211], v151 offset:6144
	ds_read_b128 v[216:219], v151 offset:7168
	global_load_lds_dwordx4 v[212:213], off
	v_lshl_add_u64 v[212:213], s[34:35], 0, v[142:143]
	s_add_i32 m0, s51, 0xe000
	s_nop 0
	global_load_lds_dwordx4 v[212:213], off
	s_waitcnt vmcnt(8)
	s_waitcnt lgkmcnt(0)
	s_barrier
	s_waitcnt lgkmcnt(0)
	v_mfma_f32_16x16x32_bf16 v[82:85], v[152:155], v[184:187], v[82:85]
	v_mfma_f32_16x16x32_bf16 v[74:77], v[160:163], v[184:187], v[74:77]
	v_mfma_f32_16x16x32_bf16 v[70:73], v[152:155], v[192:195], v[70:73]
	v_mfma_f32_16x16x32_bf16 v[62:65], v[160:163], v[192:195], v[62:65]
	v_mfma_f32_16x16x32_bf16 v[54:57], v[152:155], v[200:203], v[54:57]
	v_mfma_f32_16x16x32_bf16 v[50:53], v[160:163], v[200:203], v[50:53]
	v_mfma_f32_16x16x32_bf16 v[38:41], v[152:155], v[208:211], v[38:41]
	v_mfma_f32_16x16x32_bf16 v[34:37], v[160:163], v[208:211], v[34:37]
	v_mfma_f32_16x16x32_bf16 v[82:85], v[156:159], v[188:191], v[82:85]
	v_mfma_f32_16x16x32_bf16 v[74:77], v[164:167], v[188:191], v[74:77]
	v_mfma_f32_16x16x32_bf16 v[70:73], v[156:159], v[196:199], v[70:73]
	v_mfma_f32_16x16x32_bf16 v[62:65], v[164:167], v[196:199], v[62:65]
	v_mfma_f32_16x16x32_bf16 v[54:57], v[156:159], v[204:207], v[54:57]
	v_mfma_f32_16x16x32_bf16 v[50:53], v[164:167], v[204:207], v[50:53]
	v_mfma_f32_16x16x32_bf16 v[38:41], v[156:159], v[216:219], v[38:41]
	v_mfma_f32_16x16x32_bf16 v[34:37], v[164:167], v[216:219], v[34:37]
	v_mfma_f32_16x16x32_bf16 v[126:129], v[168:171], v[184:187], v[126:129]
	v_mfma_f32_16x16x32_bf16 v[122:125], v[176:179], v[184:187], v[122:125]
	v_mfma_f32_16x16x32_bf16 v[118:121], v[168:171], v[192:195], v[118:121]
	v_mfma_f32_16x16x32_bf16 v[114:117], v[176:179], v[192:195], v[114:117]
	v_mfma_f32_16x16x32_bf16 v[110:113], v[168:171], v[200:203], v[110:113]
	v_mfma_f32_16x16x32_bf16 v[106:109], v[176:179], v[200:203], v[106:109]
	v_mfma_f32_16x16x32_bf16 v[102:105], v[168:171], v[208:211], v[102:105]
	v_mfma_f32_16x16x32_bf16 v[98:101], v[176:179], v[208:211], v[98:101]
	v_mfma_f32_16x16x32_bf16 v[126:129], v[172:175], v[188:191], v[126:129]
	v_mfma_f32_16x16x32_bf16 v[122:125], v[180:183], v[188:191], v[122:125]
	v_mfma_f32_16x16x32_bf16 v[118:121], v[172:175], v[196:199], v[118:121]
	v_mfma_f32_16x16x32_bf16 v[114:117], v[180:183], v[196:199], v[114:117]
	v_mfma_f32_16x16x32_bf16 v[110:113], v[172:175], v[204:207], v[110:113]
	v_mfma_f32_16x16x32_bf16 v[106:109], v[180:183], v[204:207], v[106:109]
	v_mfma_f32_16x16x32_bf16 v[102:105], v[172:175], v[216:219], v[102:105]
	v_mfma_f32_16x16x32_bf16 v[98:101], v[180:183], v[216:219], v[98:101]
	s_barrier
	s_add_i32 s68, s68, s50
	v_lshl_add_u64 v[212:213], s[36:37], 0, v[130:131]
	s_mov_b32 m0, s68
	ds_read_b128 v[184:187], v151 offset:16384
	ds_read_b128 v[188:191], v151 offset:17408
	ds_read_b128 v[192:195], v151 offset:18432
	ds_read_b128 v[196:199], v151 offset:19456
	ds_read_b128 v[200:203], v151 offset:20480
	ds_read_b128 v[204:207], v151 offset:21504
	ds_read_b128 v[208:211], v151 offset:22528
	ds_read_b128 v[216:219], v151 offset:23552
	global_load_lds_dwordx4 v[212:213], off
	s_add_i32 m0, s68, 0x2000
	s_add_u32 s68, s36, 0x100000
	v_lshl_add_u64 v[220:221], s[36:37], 0, v[132:133]
	s_addc_u32 s69, s37, 0
	s_add_i32 s70, s70, s50
	global_load_lds_dwordx4 v[220:221], off
	v_lshl_add_u64 v[222:223], s[68:69], 0, v[130:131]
	s_mov_b32 m0, s70
	v_lshl_add_u64 v[224:225], s[40:41], 0, v[134:135]
	global_load_lds_dwordx4 v[222:223], off
	v_lshl_add_u64 v[222:223], s[68:69], 0, v[132:133]
	s_add_i32 m0, s70, 0x2000
	s_nop 0
	global_load_lds_dwordx4 v[222:223], off
	v_lshl_add_u64 v[222:223], s[40:41], 0, v[136:137]
	s_mov_b32 m0, s51
	s_nop 0
	global_load_lds_dwordx4 v[222:223], off
	s_mov_b32 m0, s52
	s_nop 0
	global_load_lds_dwordx4 v[224:225], off
	s_waitcnt vmcnt(8)
	s_waitcnt lgkmcnt(0)
	s_barrier
	s_waitcnt lgkmcnt(0)
	v_mfma_f32_16x16x32_bf16 v[30:33], v[152:155], v[184:187], v[30:33]
	v_mfma_f32_16x16x32_bf16 v[26:29], v[160:163], v[184:187], v[26:29]
	v_mfma_f32_16x16x32_bf16 v[22:25], v[152:155], v[192:195], v[22:25]
	v_mfma_f32_16x16x32_bf16 v[18:21], v[160:163], v[192:195], v[18:21]
	v_mfma_f32_16x16x32_bf16 v[14:17], v[152:155], v[200:203], v[14:17]
	v_mfma_f32_16x16x32_bf16 v[10:13], v[160:163], v[200:203], v[10:13]
	v_mfma_f32_16x16x32_bf16 v[6:9], v[152:155], v[208:211], v[6:9]
	v_mfma_f32_16x16x32_bf16 v[2:5], v[160:163], v[208:211], v[2:5]
	v_mfma_f32_16x16x32_bf16 v[30:33], v[156:159], v[188:191], v[30:33]
	v_mfma_f32_16x16x32_bf16 v[26:29], v[164:167], v[188:191], v[26:29]
	v_mfma_f32_16x16x32_bf16 v[22:25], v[156:159], v[196:199], v[22:25]
	v_mfma_f32_16x16x32_bf16 v[18:21], v[164:167], v[196:199], v[18:21]
	v_mfma_f32_16x16x32_bf16 v[14:17], v[156:159], v[204:207], v[14:17]
	v_mfma_f32_16x16x32_bf16 v[10:13], v[164:167], v[204:207], v[10:13]
	v_mfma_f32_16x16x32_bf16 v[6:9], v[156:159], v[216:219], v[6:9]
	v_mfma_f32_16x16x32_bf16 v[2:5], v[164:167], v[216:219], v[2:5]
	v_mfma_f32_16x16x32_bf16 v[94:97], v[168:171], v[184:187], v[94:97]
	v_mfma_f32_16x16x32_bf16 v[90:93], v[176:179], v[184:187], v[90:93]
	v_mfma_f32_16x16x32_bf16 v[86:89], v[168:171], v[192:195], v[86:89]
	v_mfma_f32_16x16x32_bf16 v[78:81], v[176:179], v[192:195], v[78:81]
	v_mfma_f32_16x16x32_bf16 v[66:69], v[168:171], v[200:203], v[66:69]
	v_mfma_f32_16x16x32_bf16 v[58:61], v[176:179], v[200:203], v[58:61]
	v_mfma_f32_16x16x32_bf16 v[46:49], v[168:171], v[208:211], v[46:49]
	v_mfma_f32_16x16x32_bf16 v[42:45], v[176:179], v[208:211], v[42:45]
	v_mfma_f32_16x16x32_bf16 v[94:97], v[172:175], v[188:191], v[94:97]
	v_mfma_f32_16x16x32_bf16 v[90:93], v[180:183], v[188:191], v[90:93]
	v_mfma_f32_16x16x32_bf16 v[86:89], v[172:175], v[196:199], v[86:89]
	v_mfma_f32_16x16x32_bf16 v[78:81], v[180:183], v[196:199], v[78:81]
	v_mfma_f32_16x16x32_bf16 v[66:69], v[172:175], v[204:207], v[66:69]
	v_mfma_f32_16x16x32_bf16 v[58:61], v[180:183], v[204:207], v[58:61]
	v_mfma_f32_16x16x32_bf16 v[46:49], v[172:175], v[216:219], v[46:49]
	v_mfma_f32_16x16x32_bf16 v[42:45], v[180:183], v[216:219], v[42:45]
	s_barrier
	s_add_i32 s68, 0, 0x18000
	v_add_u32_e32 v144, s68, v147
	s_add_i32 s69, 0, 0x1c000
	ds_read_b128 v[152:155], v144
	ds_read_b128 v[156:159], v144 offset:1024
	ds_read_b128 v[160:163], v144 offset:2048
	ds_read_b128 v[164:167], v144 offset:3072
	v_add_u32_e32 v144, s69, v147
	ds_read_b128 v[168:171], v144
	ds_read_b128 v[172:175], v144 offset:1024
	ds_read_b128 v[176:179], v144 offset:2048
	ds_read_b128 v[180:183], v144 offset:3072
	s_add_u32 s40, s40, 0x100000
	s_addc_u32 s41, s41, 0
	s_mov_b32 m0, s53
	v_lshl_add_u64 v[226:227], s[40:41], 0, v[136:137]
	ds_read_b128 v[184:187], v151 offset:32768
	ds_read_b128 v[188:191], v151 offset:33792
	ds_read_b128 v[192:195], v151 offset:34816
	ds_read_b128 v[196:199], v151 offset:35840
	ds_read_b128 v[200:203], v151 offset:36864
	ds_read_b128 v[204:207], v151 offset:37888
	ds_read_b128 v[208:211], v151 offset:38912
	ds_read_b128 v[216:219], v151 offset:39936
	global_load_lds_dwordx4 v[226:227], off
	v_lshl_add_u64 v[226:227], s[40:41], 0, v[134:135]
	s_mov_b32 m0, s54
	s_nop 0
	global_load_lds_dwordx4 v[226:227], off
	s_waitcnt vmcnt(8)
	s_waitcnt lgkmcnt(0)
	s_barrier
	s_waitcnt lgkmcnt(0)
	v_mfma_f32_16x16x32_bf16 v[82:85], v[152:155], v[184:187], v[82:85]
	v_mfma_f32_16x16x32_bf16 v[74:77], v[160:163], v[184:187], v[74:77]
	v_mfma_f32_16x16x32_bf16 v[70:73], v[152:155], v[192:195], v[70:73]
	v_mfma_f32_16x16x32_bf16 v[62:65], v[160:163], v[192:195], v[62:65]
	v_mfma_f32_16x16x32_bf16 v[54:57], v[152:155], v[200:203], v[54:57]
	v_mfma_f32_16x16x32_bf16 v[50:53], v[160:163], v[200:203], v[50:53]
	v_mfma_f32_16x16x32_bf16 v[38:41], v[152:155], v[208:211], v[38:41]
	v_mfma_f32_16x16x32_bf16 v[34:37], v[160:163], v[208:211], v[34:37]
	v_mfma_f32_16x16x32_bf16 v[82:85], v[156:159], v[188:191], v[82:85]
	v_mfma_f32_16x16x32_bf16 v[74:77], v[164:167], v[188:191], v[74:77]
	v_mfma_f32_16x16x32_bf16 v[70:73], v[156:159], v[196:199], v[70:73]
	v_mfma_f32_16x16x32_bf16 v[62:65], v[164:167], v[196:199], v[62:65]
	v_mfma_f32_16x16x32_bf16 v[54:57], v[156:159], v[204:207], v[54:57]
	v_mfma_f32_16x16x32_bf16 v[50:53], v[164:167], v[204:207], v[50:53]
	v_mfma_f32_16x16x32_bf16 v[38:41], v[156:159], v[216:219], v[38:41]
	v_mfma_f32_16x16x32_bf16 v[34:37], v[164:167], v[216:219], v[34:37]
	v_mfma_f32_16x16x32_bf16 v[126:129], v[168:171], v[184:187], v[126:129]
	v_mfma_f32_16x16x32_bf16 v[122:125], v[176:179], v[184:187], v[122:125]
	v_mfma_f32_16x16x32_bf16 v[118:121], v[168:171], v[192:195], v[118:121]
	v_mfma_f32_16x16x32_bf16 v[114:117], v[176:179], v[192:195], v[114:117]
	v_mfma_f32_16x16x32_bf16 v[110:113], v[168:171], v[200:203], v[110:113]
	v_mfma_f32_16x16x32_bf16 v[106:109], v[176:179], v[200:203], v[106:109]
	v_mfma_f32_16x16x32_bf16 v[102:105], v[168:171], v[208:211], v[102:105]
	v_mfma_f32_16x16x32_bf16 v[98:101], v[176:179], v[208:211], v[98:101]
	v_mfma_f32_16x16x32_bf16 v[126:129], v[172:175], v[188:191], v[126:129]
	v_mfma_f32_16x16x32_bf16 v[122:125], v[180:183], v[188:191], v[122:125]
	v_mfma_f32_16x16x32_bf16 v[118:121], v[172:175], v[196:199], v[118:121]
	v_mfma_f32_16x16x32_bf16 v[114:117], v[180:183], v[196:199], v[114:117]
	v_mfma_f32_16x16x32_bf16 v[110:113], v[172:175], v[204:207], v[110:113]
	v_mfma_f32_16x16x32_bf16 v[106:109], v[180:183], v[204:207], v[106:109]
	v_mfma_f32_16x16x32_bf16 v[102:105], v[172:175], v[216:219], v[102:105]
	v_mfma_f32_16x16x32_bf16 v[98:101], v[180:183], v[216:219], v[98:101]
	s_barrier
	s_add_i32 s40, s68, s50
	v_lshl_add_u64 v[212:213], v[212:213], 0, s[18:19]
	s_mov_b32 m0, s40
	ds_read_b128 v[184:187], v151 offset:49152
	ds_read_b128 v[188:191], v151 offset:50176
	ds_read_b128 v[192:195], v151 offset:51200
	ds_read_b128 v[196:199], v151 offset:52224
	ds_read_b128 v[200:203], v151 offset:53248
	ds_read_b128 v[204:207], v151 offset:54272
	ds_read_b128 v[208:211], v151 offset:55296
	ds_read_b128 v[216:219], v151 offset:56320
	global_load_lds_dwordx4 v[212:213], off
	s_add_i32 m0, s40, 0x2000
	s_add_u32 s36, s36, 0x100080
	v_lshl_add_u64 v[212:213], v[220:221], 0, s[18:19]
	s_addc_u32 s37, s37, 0
	s_add_i32 s40, s69, s50
	global_load_lds_dwordx4 v[212:213], off
	v_lshl_add_u64 v[212:213], s[36:37], 0, v[130:131]
	s_mov_b32 m0, s40
	s_nop 0
	global_load_lds_dwordx4 v[212:213], off
	v_lshl_add_u64 v[212:213], s[36:37], 0, v[132:133]
	s_add_i32 m0, s40, 0x2000
	s_nop 0
	global_load_lds_dwordx4 v[212:213], off
	v_lshl_add_u64 v[212:213], v[222:223], 0, s[18:19]
	s_mov_b32 m0, s30
	s_nop 0
	global_load_lds_dwordx4 v[212:213], off
	v_lshl_add_u64 v[212:213], v[224:225], 0, s[18:19]
	s_mov_b32 m0, s55
	s_nop 0
	global_load_lds_dwordx4 v[212:213], off
	s_waitcnt vmcnt(8)
	s_waitcnt lgkmcnt(0)
	s_barrier
	s_waitcnt lgkmcnt(0)
	v_mfma_f32_16x16x32_bf16 v[30:33], v[152:155], v[184:187], v[30:33]
	v_mfma_f32_16x16x32_bf16 v[26:29], v[160:163], v[184:187], v[26:29]
	v_mfma_f32_16x16x32_bf16 v[22:25], v[152:155], v[192:195], v[22:25]
	v_mfma_f32_16x16x32_bf16 v[18:21], v[160:163], v[192:195], v[18:21]
	v_mfma_f32_16x16x32_bf16 v[14:17], v[152:155], v[200:203], v[14:17]
	v_mfma_f32_16x16x32_bf16 v[10:13], v[160:163], v[200:203], v[10:13]
	v_mfma_f32_16x16x32_bf16 v[6:9], v[152:155], v[208:211], v[6:9]
	v_mfma_f32_16x16x32_bf16 v[2:5], v[160:163], v[208:211], v[2:5]
	s_add_i32 s67, s67, 2
	v_mfma_f32_16x16x32_bf16 v[30:33], v[156:159], v[188:191], v[30:33]
	s_add_u32 s34, s34, 0x100
	v_mfma_f32_16x16x32_bf16 v[26:29], v[164:167], v[188:191], v[26:29]
	s_addc_u32 s35, s35, 0
	v_mfma_f32_16x16x32_bf16 v[22:25], v[156:159], v[196:199], v[22:25]
	s_add_u32 s63, s63, 0x100
	v_mfma_f32_16x16x32_bf16 v[18:21], v[164:167], v[196:199], v[18:21]
	s_addc_u32 s66, s66, 0
	v_mfma_f32_16x16x32_bf16 v[14:17], v[156:159], v[204:207], v[14:17]
	s_cmp_gt_u32 s67, 61
	v_mfma_f32_16x16x32_bf16 v[10:13], v[164:167], v[204:207], v[10:13]
	v_mfma_f32_16x16x32_bf16 v[6:9], v[156:159], v[216:219], v[6:9]
	v_mfma_f32_16x16x32_bf16 v[2:5], v[164:167], v[216:219], v[2:5]
	v_mfma_f32_16x16x32_bf16 v[94:97], v[168:171], v[184:187], v[94:97]
	v_mfma_f32_16x16x32_bf16 v[90:93], v[176:179], v[184:187], v[90:93]
	v_mfma_f32_16x16x32_bf16 v[86:89], v[168:171], v[192:195], v[86:89]
	v_mfma_f32_16x16x32_bf16 v[78:81], v[176:179], v[192:195], v[78:81]
	v_mfma_f32_16x16x32_bf16 v[66:69], v[168:171], v[200:203], v[66:69]
	v_mfma_f32_16x16x32_bf16 v[58:61], v[176:179], v[200:203], v[58:61]
	v_mfma_f32_16x16x32_bf16 v[46:49], v[168:171], v[208:211], v[46:49]
	v_mfma_f32_16x16x32_bf16 v[42:45], v[176:179], v[208:211], v[42:45]
	v_mfma_f32_16x16x32_bf16 v[94:97], v[172:175], v[188:191], v[94:97]
	v_mfma_f32_16x16x32_bf16 v[90:93], v[180:183], v[188:191], v[90:93]
	v_mfma_f32_16x16x32_bf16 v[86:89], v[172:175], v[196:199], v[86:89]
	v_mfma_f32_16x16x32_bf16 v[78:81], v[180:183], v[196:199], v[78:81]
	v_mfma_f32_16x16x32_bf16 v[66:69], v[172:175], v[204:207], v[66:69]
	v_mfma_f32_16x16x32_bf16 v[58:61], v[180:183], v[204:207], v[58:61]
	v_mfma_f32_16x16x32_bf16 v[46:49], v[172:175], v[216:219], v[46:49]
	v_mfma_f32_16x16x32_bf16 v[42:45], v[180:183], v[216:219], v[42:45]
	s_barrier
	s_cbranch_scc0 .LBB0_132
	s_and_b64 vcc, exec, s[12:13]
	s_cbranch_vccz .LBB0_135
	s_barrier

.LBB0_872:
	s_add_u32 s26, s24, 0xfff00080
	s_addc_u32 s27, s25, -1
	s_add_i32 s56, 0, 0x10000
	s_cmp_eq_u32 s55, 60
	s_cselect_b32 s29, s13, s27
	s_cselect_b32 s28, s51, s26
	v_add_u32_e32 v148, s56, v152
	s_cselect_b32 s27, s9, s54
	s_cselect_b32 s26, s52, s53
	s_add_i32 s58, 0, 0x14000
	ds_read_b128 v[144:147], v148
	ds_read_b128 v[156:159], v148 offset:1024
	ds_read_b128 v[160:163], v148 offset:2048
	ds_read_b128 v[164:167], v148 offset:3072
	v_add_u32_e32 v148, s58, v152
	ds_read_b128 v[168:171], v148
	ds_read_b128 v[172:175], v148 offset:1024
	ds_read_b128 v[176:179], v148 offset:2048
	ds_read_b128 v[180:183], v148 offset:3072
	v_lshl_add_u64 v[148:149], s[24:25], 0, v[140:141]
	s_add_i32 m0, s41, 0xc000
	ds_read_b128 v[184:187], v154
	ds_read_b128 v[188:191], v154 offset:1024
	ds_read_b128 v[192:195], v154 offset:2048
	ds_read_b128 v[196:199], v154 offset:3072
	ds_read_b128 v[200:203], v154 offset:4096
	ds_read_b128 v[204:207], v154 offset:5120
	ds_read_b128 v[208:211], v154 offset:6144
	ds_read_b128 v[216:219], v154 offset:7168
	global_load_lds_dwordx4 v[148:149], off
	v_lshl_add_u64 v[148:149], s[24:25], 0, v[142:143]
	s_add_i32 m0, s41, 0xe000
	s_nop 0
	global_load_lds_dwordx4 v[148:149], off
	s_waitcnt vmcnt(8)
	s_waitcnt lgkmcnt(0)
	s_barrier
	s_waitcnt lgkmcnt(0)
	v_mfma_f32_16x16x32_bf16 v[126:129], v[144:147], v[184:187], v[126:129]
	v_mfma_f32_16x16x32_bf16 v[122:125], v[160:163], v[184:187], v[122:125]
	v_mfma_f32_16x16x32_bf16 v[110:113], v[144:147], v[192:195], v[110:113]
	v_mfma_f32_16x16x32_bf16 v[106:109], v[160:163], v[192:195], v[106:109]
	v_mfma_f32_16x16x32_bf16 v[94:97], v[144:147], v[200:203], v[94:97]
	v_mfma_f32_16x16x32_bf16 v[90:93], v[160:163], v[200:203], v[90:93]
	v_mfma_f32_16x16x32_bf16 v[78:81], v[144:147], v[208:211], v[78:81]
	v_mfma_f32_16x16x32_bf16 v[74:77], v[160:163], v[208:211], v[74:77]
	v_mfma_f32_16x16x32_bf16 v[126:129], v[156:159], v[188:191], v[126:129]
	v_mfma_f32_16x16x32_bf16 v[122:125], v[164:167], v[188:191], v[122:125]
	v_mfma_f32_16x16x32_bf16 v[110:113], v[156:159], v[196:199], v[110:113]
	v_mfma_f32_16x16x32_bf16 v[106:109], v[164:167], v[196:199], v[106:109]
	v_mfma_f32_16x16x32_bf16 v[94:97], v[156:159], v[204:207], v[94:97]
	v_mfma_f32_16x16x32_bf16 v[90:93], v[164:167], v[204:207], v[90:93]
	v_mfma_f32_16x16x32_bf16 v[78:81], v[156:159], v[216:219], v[78:81]
	v_mfma_f32_16x16x32_bf16 v[74:77], v[164:167], v[216:219], v[74:77]
	v_mfma_f32_16x16x32_bf16 v[118:121], v[168:171], v[184:187], v[118:121]
	v_mfma_f32_16x16x32_bf16 v[114:117], v[176:179], v[184:187], v[114:117]
	v_mfma_f32_16x16x32_bf16 v[102:105], v[168:171], v[192:195], v[102:105]
	v_mfma_f32_16x16x32_bf16 v[98:101], v[176:179], v[192:195], v[98:101]
	v_mfma_f32_16x16x32_bf16 v[86:89], v[168:171], v[200:203], v[86:89]
	v_mfma_f32_16x16x32_bf16 v[82:85], v[176:179], v[200:203], v[82:85]
	v_mfma_f32_16x16x32_bf16 v[70:73], v[168:171], v[208:211], v[70:73]
	v_mfma_f32_16x16x32_bf16 v[66:69], v[176:179], v[208:211], v[66:69]
	v_mfma_f32_16x16x32_bf16 v[118:121], v[172:175], v[188:191], v[118:121]
	v_mfma_f32_16x16x32_bf16 v[114:117], v[180:183], v[188:191], v[114:117]
	v_mfma_f32_16x16x32_bf16 v[102:105], v[172:175], v[196:199], v[102:105]
	v_mfma_f32_16x16x32_bf16 v[98:101], v[180:183], v[196:199], v[98:101]
	v_mfma_f32_16x16x32_bf16 v[86:89], v[172:175], v[204:207], v[86:89]
	v_mfma_f32_16x16x32_bf16 v[82:85], v[180:183], v[204:207], v[82:85]
	v_mfma_f32_16x16x32_bf16 v[70:73], v[172:175], v[216:219], v[70:73]
	v_mfma_f32_16x16x32_bf16 v[66:69], v[180:183], v[216:219], v[66:69]
	s_barrier
	s_add_i32 s56, s56, s40
	v_lshl_add_u64 v[148:149], s[26:27], 0, v[130:131]
	s_mov_b32 m0, s56
	ds_read_b128 v[184:187], v154 offset:16384
	ds_read_b128 v[188:191], v154 offset:17408
	ds_read_b128 v[192:195], v154 offset:18432
	ds_read_b128 v[196:199], v154 offset:19456
	ds_read_b128 v[200:203], v154 offset:20480
	ds_read_b128 v[204:207], v154 offset:21504
	ds_read_b128 v[208:211], v154 offset:22528
	ds_read_b128 v[216:219], v154 offset:23552
	global_load_lds_dwordx4 v[148:149], off
	s_add_i32 m0, s56, 0x2000
	s_add_u32 s56, s26, 0x100000
	v_lshl_add_u64 v[212:213], s[26:27], 0, v[132:133]
	s_addc_u32 s57, s27, 0
	s_add_i32 s58, s58, s40
	global_load_lds_dwordx4 v[212:213], off
	v_lshl_add_u64 v[220:221], s[56:57], 0, v[130:131]
	s_mov_b32 m0, s58
	v_lshl_add_u64 v[222:223], s[28:29], 0, v[134:135]
	global_load_lds_dwordx4 v[220:221], off
	v_lshl_add_u64 v[220:221], s[56:57], 0, v[132:133]
	s_add_i32 m0, s58, 0x2000
	s_nop 0
	global_load_lds_dwordx4 v[220:221], off
	v_lshl_add_u64 v[220:221], s[28:29], 0, v[136:137]
	s_mov_b32 m0, s41
	s_nop 0
	global_load_lds_dwordx4 v[220:221], off
	s_mov_b32 m0, s44
	s_nop 0
	global_load_lds_dwordx4 v[222:223], off
	s_waitcnt vmcnt(8)
	s_waitcnt lgkmcnt(0)
	s_barrier
	s_waitcnt lgkmcnt(0)
	v_mfma_f32_16x16x32_bf16 v[62:65], v[144:147], v[184:187], v[62:65]
	v_mfma_f32_16x16x32_bf16 v[58:61], v[160:163], v[184:187], v[58:61]
	v_mfma_f32_16x16x32_bf16 v[46:49], v[144:147], v[192:195], v[46:49]
	v_mfma_f32_16x16x32_bf16 v[42:45], v[160:163], v[192:195], v[42:45]
	v_mfma_f32_16x16x32_bf16 v[30:33], v[144:147], v[200:203], v[30:33]
	v_mfma_f32_16x16x32_bf16 v[26:29], v[160:163], v[200:203], v[26:29]
	v_mfma_f32_16x16x32_bf16 v[14:17], v[144:147], v[208:211], v[14:17]
	v_mfma_f32_16x16x32_bf16 v[10:13], v[160:163], v[208:211], v[10:13]
	v_mfma_f32_16x16x32_bf16 v[62:65], v[156:159], v[188:191], v[62:65]
	v_mfma_f32_16x16x32_bf16 v[58:61], v[164:167], v[188:191], v[58:61]
	v_mfma_f32_16x16x32_bf16 v[46:49], v[156:159], v[196:199], v[46:49]
	v_mfma_f32_16x16x32_bf16 v[42:45], v[164:167], v[196:199], v[42:45]
	v_mfma_f32_16x16x32_bf16 v[30:33], v[156:159], v[204:207], v[30:33]
	v_mfma_f32_16x16x32_bf16 v[26:29], v[164:167], v[204:207], v[26:29]
	v_mfma_f32_16x16x32_bf16 v[14:17], v[156:159], v[216:219], v[14:17]
	v_mfma_f32_16x16x32_bf16 v[10:13], v[164:167], v[216:219], v[10:13]
	v_mfma_f32_16x16x32_bf16 v[54:57], v[168:171], v[184:187], v[54:57]
	v_mfma_f32_16x16x32_bf16 v[50:53], v[176:179], v[184:187], v[50:53]
	v_mfma_f32_16x16x32_bf16 v[38:41], v[168:171], v[192:195], v[38:41]
	v_mfma_f32_16x16x32_bf16 v[34:37], v[176:179], v[192:195], v[34:37]
	v_mfma_f32_16x16x32_bf16 v[22:25], v[168:171], v[200:203], v[22:25]
	v_mfma_f32_16x16x32_bf16 v[18:21], v[176:179], v[200:203], v[18:21]
	v_mfma_f32_16x16x32_bf16 v[6:9], v[168:171], v[208:211], v[6:9]
	v_mfma_f32_16x16x32_bf16 v[2:5], v[176:179], v[208:211], v[2:5]
	v_mfma_f32_16x16x32_bf16 v[54:57], v[172:175], v[188:191], v[54:57]
	v_mfma_f32_16x16x32_bf16 v[50:53], v[180:183], v[188:191], v[50:53]
	v_mfma_f32_16x16x32_bf16 v[38:41], v[172:175], v[196:199], v[38:41]
	v_mfma_f32_16x16x32_bf16 v[34:37], v[180:183], v[196:199], v[34:37]
	v_mfma_f32_16x16x32_bf16 v[22:25], v[172:175], v[204:207], v[22:25]
	v_mfma_f32_16x16x32_bf16 v[18:21], v[180:183], v[204:207], v[18:21]
	v_mfma_f32_16x16x32_bf16 v[6:9], v[172:175], v[216:219], v[6:9]
	v_mfma_f32_16x16x32_bf16 v[2:5], v[180:183], v[216:219], v[2:5]
	s_barrier
	s_add_i32 s56, 0, 0x18000
	v_add_u32_e32 v155, s56, v152
	s_add_i32 s57, 0, 0x1c000
	ds_read_b128 v[144:147], v155
	ds_read_b128 v[156:159], v155 offset:1024
	ds_read_b128 v[160:163], v155 offset:2048
	ds_read_b128 v[164:167], v155 offset:3072
	v_add_u32_e32 v155, s57, v152
	ds_read_b128 v[168:171], v155
	ds_read_b128 v[172:175], v155 offset:1024
	ds_read_b128 v[176:179], v155 offset:2048
	ds_read_b128 v[180:183], v155 offset:3072
	s_add_u32 s28, s28, 0x100000
	s_addc_u32 s29, s29, 0
	s_mov_b32 m0, s45
	v_lshl_add_u64 v[224:225], s[28:29], 0, v[136:137]
	ds_read_b128 v[184:187], v154 offset:32768
	ds_read_b128 v[188:191], v154 offset:33792
	ds_read_b128 v[192:195], v154 offset:34816
	ds_read_b128 v[196:199], v154 offset:35840
	ds_read_b128 v[200:203], v154 offset:36864
	ds_read_b128 v[204:207], v154 offset:37888
	ds_read_b128 v[208:211], v154 offset:38912
	ds_read_b128 v[216:219], v154 offset:39936
	global_load_lds_dwordx4 v[224:225], off
	v_lshl_add_u64 v[224:225], s[28:29], 0, v[134:135]
	s_mov_b32 m0, s46
	s_nop 0
	global_load_lds_dwordx4 v[224:225], off
	s_waitcnt vmcnt(8)
	s_waitcnt lgkmcnt(0)
	s_barrier
	s_waitcnt lgkmcnt(0)
	v_mfma_f32_16x16x32_bf16 v[126:129], v[144:147], v[184:187], v[126:129]
	v_mfma_f32_16x16x32_bf16 v[122:125], v[160:163], v[184:187], v[122:125]
	v_mfma_f32_16x16x32_bf16 v[110:113], v[144:147], v[192:195], v[110:113]
	v_mfma_f32_16x16x32_bf16 v[106:109], v[160:163], v[192:195], v[106:109]
	v_mfma_f32_16x16x32_bf16 v[94:97], v[144:147], v[200:203], v[94:97]
	v_mfma_f32_16x16x32_bf16 v[90:93], v[160:163], v[200:203], v[90:93]
	v_mfma_f32_16x16x32_bf16 v[78:81], v[144:147], v[208:211], v[78:81]
	v_mfma_f32_16x16x32_bf16 v[74:77], v[160:163], v[208:211], v[74:77]
	v_mfma_f32_16x16x32_bf16 v[126:129], v[156:159], v[188:191], v[126:129]
	v_mfma_f32_16x16x32_bf16 v[122:125], v[164:167], v[188:191], v[122:125]
	v_mfma_f32_16x16x32_bf16 v[110:113], v[156:159], v[196:199], v[110:113]
	v_mfma_f32_16x16x32_bf16 v[106:109], v[164:167], v[196:199], v[106:109]
	v_mfma_f32_16x16x32_bf16 v[94:97], v[156:159], v[204:207], v[94:97]
	v_mfma_f32_16x16x32_bf16 v[90:93], v[164:167], v[204:207], v[90:93]
	v_mfma_f32_16x16x32_bf16 v[78:81], v[156:159], v[216:219], v[78:81]
	v_mfma_f32_16x16x32_bf16 v[74:77], v[164:167], v[216:219], v[74:77]
	v_mfma_f32_16x16x32_bf16 v[118:121], v[168:171], v[184:187], v[118:121]
	v_mfma_f32_16x16x32_bf16 v[114:117], v[176:179], v[184:187], v[114:117]
	v_mfma_f32_16x16x32_bf16 v[102:105], v[168:171], v[192:195], v[102:105]
	v_mfma_f32_16x16x32_bf16 v[98:101], v[176:179], v[192:195], v[98:101]
	v_mfma_f32_16x16x32_bf16 v[86:89], v[168:171], v[200:203], v[86:89]
	v_mfma_f32_16x16x32_bf16 v[82:85], v[176:179], v[200:203], v[82:85]
	v_mfma_f32_16x16x32_bf16 v[70:73], v[168:171], v[208:211], v[70:73]
	v_mfma_f32_16x16x32_bf16 v[66:69], v[176:179], v[208:211], v[66:69]
	v_mfma_f32_16x16x32_bf16 v[118:121], v[172:175], v[188:191], v[118:121]
	v_mfma_f32_16x16x32_bf16 v[114:117], v[180:183], v[188:191], v[114:117]
	v_mfma_f32_16x16x32_bf16 v[102:105], v[172:175], v[196:199], v[102:105]
	v_mfma_f32_16x16x32_bf16 v[98:101], v[180:183], v[196:199], v[98:101]
	v_mfma_f32_16x16x32_bf16 v[86:89], v[172:175], v[204:207], v[86:89]
	v_mfma_f32_16x16x32_bf16 v[82:85], v[180:183], v[204:207], v[82:85]
	v_mfma_f32_16x16x32_bf16 v[70:73], v[172:175], v[216:219], v[70:73]
	v_mfma_f32_16x16x32_bf16 v[66:69], v[180:183], v[216:219], v[66:69]
	s_barrier
	s_add_i32 s28, s56, s40
	v_lshl_add_u64 v[148:149], v[148:149], 0, s[18:19]
	s_mov_b32 m0, s28
	ds_read_b128 v[184:187], v154 offset:49152
	ds_read_b128 v[188:191], v154 offset:50176
	ds_read_b128 v[192:195], v154 offset:51200
	ds_read_b128 v[196:199], v154 offset:52224
	ds_read_b128 v[200:203], v154 offset:53248
	ds_read_b128 v[204:207], v154 offset:54272
	ds_read_b128 v[208:211], v154 offset:55296
	ds_read_b128 v[216:219], v154 offset:56320
	global_load_lds_dwordx4 v[148:149], off
	s_add_i32 m0, s28, 0x2000
	s_add_u32 s26, s26, 0x100080
	v_lshl_add_u64 v[148:149], v[212:213], 0, s[18:19]
	s_addc_u32 s27, s27, 0
	s_add_i32 s28, s57, s40
	global_load_lds_dwordx4 v[148:149], off
	v_lshl_add_u64 v[148:149], s[26:27], 0, v[130:131]
	s_mov_b32 m0, s28
	s_nop 0
	global_load_lds_dwordx4 v[148:149], off
	v_lshl_add_u64 v[148:149], s[26:27], 0, v[132:133]
	s_add_i32 m0, s28, 0x2000
	s_nop 0
	global_load_lds_dwordx4 v[148:149], off
	v_lshl_add_u64 v[148:149], v[220:221], 0, s[18:19]
	s_mov_b32 m0, s30
	s_nop 0
	global_load_lds_dwordx4 v[148:149], off
	v_lshl_add_u64 v[148:149], v[222:223], 0, s[18:19]
	s_mov_b32 m0, s47
	s_nop 0
	global_load_lds_dwordx4 v[148:149], off
	s_waitcnt vmcnt(8)
	s_waitcnt lgkmcnt(0)
	s_barrier
	s_waitcnt lgkmcnt(0)
	v_mfma_f32_16x16x32_bf16 v[62:65], v[144:147], v[184:187], v[62:65]
	v_mfma_f32_16x16x32_bf16 v[58:61], v[160:163], v[184:187], v[58:61]
	v_mfma_f32_16x16x32_bf16 v[46:49], v[144:147], v[192:195], v[46:49]
	v_mfma_f32_16x16x32_bf16 v[42:45], v[160:163], v[192:195], v[42:45]
	v_mfma_f32_16x16x32_bf16 v[30:33], v[144:147], v[200:203], v[30:33]
	v_mfma_f32_16x16x32_bf16 v[26:29], v[160:163], v[200:203], v[26:29]
	v_mfma_f32_16x16x32_bf16 v[14:17], v[144:147], v[208:211], v[14:17]
	v_mfma_f32_16x16x32_bf16 v[10:13], v[160:163], v[208:211], v[10:13]
	s_add_i32 s55, s55, 2
	v_mfma_f32_16x16x32_bf16 v[62:65], v[156:159], v[188:191], v[62:65]
	s_add_u32 s24, s24, 0x100
	v_mfma_f32_16x16x32_bf16 v[58:61], v[164:167], v[188:191], v[58:61]
	s_addc_u32 s25, s25, 0
	v_mfma_f32_16x16x32_bf16 v[46:49], v[156:159], v[196:199], v[46:49]
	s_add_u32 s53, s53, 0x100
	v_mfma_f32_16x16x32_bf16 v[42:45], v[164:167], v[196:199], v[42:45]
	s_addc_u32 s54, s54, 0
	v_mfma_f32_16x16x32_bf16 v[30:33], v[156:159], v[204:207], v[30:33]
	s_cmp_gt_u32 s55, 61
	v_mfma_f32_16x16x32_bf16 v[26:29], v[164:167], v[204:207], v[26:29]
	v_mfma_f32_16x16x32_bf16 v[14:17], v[156:159], v[216:219], v[14:17]
	v_mfma_f32_16x16x32_bf16 v[10:13], v[164:167], v[216:219], v[10:13]
	v_mfma_f32_16x16x32_bf16 v[54:57], v[168:171], v[184:187], v[54:57]
	v_mfma_f32_16x16x32_bf16 v[50:53], v[176:179], v[184:187], v[50:53]
	v_mfma_f32_16x16x32_bf16 v[38:41], v[168:171], v[192:195], v[38:41]
	v_mfma_f32_16x16x32_bf16 v[34:37], v[176:179], v[192:195], v[34:37]
	v_mfma_f32_16x16x32_bf16 v[22:25], v[168:171], v[200:203], v[22:25]
	v_mfma_f32_16x16x32_bf16 v[18:21], v[176:179], v[200:203], v[18:21]
	v_mfma_f32_16x16x32_bf16 v[6:9], v[168:171], v[208:211], v[6:9]
	v_mfma_f32_16x16x32_bf16 v[2:5], v[176:179], v[208:211], v[2:5]
	v_mfma_f32_16x16x32_bf16 v[54:57], v[172:175], v[188:191], v[54:57]
	v_mfma_f32_16x16x32_bf16 v[50:53], v[180:183], v[188:191], v[50:53]
	v_mfma_f32_16x16x32_bf16 v[38:41], v[172:175], v[196:199], v[38:41]
	v_mfma_f32_16x16x32_bf16 v[34:37], v[180:183], v[196:199], v[34:37]
	v_mfma_f32_16x16x32_bf16 v[22:25], v[172:175], v[204:207], v[22:25]
	v_mfma_f32_16x16x32_bf16 v[18:21], v[180:183], v[204:207], v[18:21]
	v_mfma_f32_16x16x32_bf16 v[6:9], v[172:175], v[216:219], v[6:9]
	v_mfma_f32_16x16x32_bf16 v[2:5], v[180:183], v[216:219], v[2:5]
	s_barrier
	s_cbranch_scc0 .LBB0_872
	s_and_b64 vcc, exec, s[6:7]
	s_cbranch_vccz .LBB0_875
	s_barrier

.LBB0_1024:
	s_add_u32 s46, s2, 0xfff00080
	s_addc_u32 s47, s3, -1
	s_add_i32 s83, 0, 0x10000
	s_cmp_eq_u32 s82, 60
	s_cselect_b32 s59, s30, s47
	s_cselect_b32 s58, s53, s46
	s_cselect_b32 s47, s51, s81
	s_cselect_b32 s46, s79, s80
	s_add_i32 s86, 0, 0x14000
	v_add_u32_e32 v74, s83, v244
	v_add_u32_e32 v94, s86, v244
	ds_read_b128 v[62:65], v74
	ds_read_b128 v[66:69], v74 offset:1024
	ds_read_b128 v[70:73], v74 offset:2048
	ds_read_b128 v[74:77], v74 offset:3072
	ds_read_b128 v[78:81], v94
	ds_read_b128 v[82:85], v94 offset:1024
	ds_read_b128 v[90:93], v94 offset:2048
	ds_read_b128 v[94:97], v94 offset:3072
	v_lshl_add_u64 v[196:197], s[2:3], 0, v[222:223]
	s_add_i32 m0, s67, 0xc000
	ds_read_b128 v[98:101], v250
	ds_read_b128 v[102:105], v250 offset:1024
	ds_read_b128 v[106:109], v250 offset:2048
	ds_read_b128 v[110:113], v250 offset:3072
	ds_read_b128 v[180:183], v250 offset:4096
	ds_read_b128 v[184:187], v250 offset:5120
	ds_read_b128 v[188:191], v250 offset:6144
	ds_read_b128 v[192:195], v250 offset:7168
	global_load_lds_dwordx4 v[196:197], off
	v_lshl_add_u64 v[196:197], s[2:3], 0, v[224:225]
	s_add_i32 m0, s67, 0xe000
	s_nop 0
	global_load_lds_dwordx4 v[196:197], off
	s_waitcnt vmcnt(8)
	s_waitcnt lgkmcnt(0)
	s_barrier
	s_waitcnt lgkmcnt(0)
	v_mfma_f32_16x16x32_bf16 v[176:179], v[62:65], v[98:101], v[176:179]
	v_mfma_f32_16x16x32_bf16 v[168:171], v[70:73], v[98:101], v[168:171]
	v_mfma_f32_16x16x32_bf16 v[160:163], v[62:65], v[106:109], v[160:163]
	v_mfma_f32_16x16x32_bf16 v[152:155], v[70:73], v[106:109], v[152:155]
	v_mfma_f32_16x16x32_bf16 v[144:147], v[62:65], v[180:183], v[144:147]
	v_mfma_f32_16x16x32_bf16 v[136:139], v[70:73], v[180:183], v[136:139]
	v_mfma_f32_16x16x32_bf16 v[126:129], v[62:65], v[188:191], v[126:129]
	v_mfma_f32_16x16x32_bf16 v[118:121], v[70:73], v[188:191], v[118:121]
	v_mfma_f32_16x16x32_bf16 v[176:179], v[66:69], v[102:105], v[176:179]
	v_mfma_f32_16x16x32_bf16 v[168:171], v[74:77], v[102:105], v[168:171]
	v_mfma_f32_16x16x32_bf16 v[160:163], v[66:69], v[110:113], v[160:163]
	v_mfma_f32_16x16x32_bf16 v[152:155], v[74:77], v[110:113], v[152:155]
	v_mfma_f32_16x16x32_bf16 v[144:147], v[66:69], v[184:187], v[144:147]
	v_mfma_f32_16x16x32_bf16 v[136:139], v[74:77], v[184:187], v[136:139]
	v_mfma_f32_16x16x32_bf16 v[126:129], v[66:69], v[192:195], v[126:129]
	v_mfma_f32_16x16x32_bf16 v[118:121], v[74:77], v[192:195], v[118:121]
	v_mfma_f32_16x16x32_bf16 v[172:175], v[78:81], v[98:101], v[172:175]
	v_mfma_f32_16x16x32_bf16 v[98:101], v[90:93], v[98:101], v[164:167]
	v_mfma_f32_16x16x32_bf16 v[172:175], v[82:85], v[102:105], v[172:175]
	v_mfma_f32_16x16x32_bf16 v[98:101], v[94:97], v[102:105], v[98:101]
	v_mfma_f32_16x16x32_bf16 v[102:105], v[78:81], v[106:109], v[156:159]
	v_mfma_f32_16x16x32_bf16 v[106:109], v[90:93], v[106:109], v[148:151]
	v_mfma_f32_16x16x32_bf16 v[132:135], v[90:93], v[180:183], v[132:135]
	v_mfma_f32_16x16x32_bf16 v[122:125], v[78:81], v[188:191], v[122:125]
	v_mfma_f32_16x16x32_bf16 v[114:117], v[90:93], v[188:191], v[114:117]
	v_mfma_f32_16x16x32_bf16 v[102:105], v[82:85], v[110:113], v[102:105]
	v_mfma_f32_16x16x32_bf16 v[106:109], v[94:97], v[110:113], v[106:109]
	v_mfma_f32_16x16x32_bf16 v[110:113], v[78:81], v[180:183], v[140:143]
	v_mfma_f32_16x16x32_bf16 v[132:135], v[94:97], v[184:187], v[132:135]
	v_mfma_f32_16x16x32_bf16 v[122:125], v[82:85], v[192:195], v[122:125]
	v_mfma_f32_16x16x32_bf16 v[114:117], v[94:97], v[192:195], v[114:117]
	v_mfma_f32_16x16x32_bf16 v[110:113], v[82:85], v[184:187], v[110:113]
	s_barrier
	s_add_i32 s83, s83, s66
	v_lshl_add_u64 v[204:205], s[46:47], 0, v[130:131]
	s_mov_b32 m0, s83
	ds_read_b128 v[140:143], v250 offset:16384
	ds_read_b128 v[148:151], v250 offset:17408
	ds_read_b128 v[156:159], v250 offset:18432
	ds_read_b128 v[164:167], v250 offset:19456
	ds_read_b128 v[180:183], v250 offset:20480
	ds_read_b128 v[184:187], v250 offset:21504
	ds_read_b128 v[188:191], v250 offset:22528
	ds_read_b128 v[192:195], v250 offset:23552
	global_load_lds_dwordx4 v[204:205], off
	s_add_i32 m0, s83, 0x2000
	s_add_u32 s84, s46, 0x100000
	v_lshl_add_u64 v[206:207], s[46:47], 0, v[216:217]
	s_addc_u32 s85, s47, 0
	s_add_i32 s83, s86, s66
	global_load_lds_dwordx4 v[206:207], off
	v_lshl_add_u64 v[196:197], s[84:85], 0, v[130:131]
	s_mov_b32 m0, s83
	v_lshl_add_u64 v[208:209], s[58:59], 0, v[220:221]
	global_load_lds_dwordx4 v[196:197], off
	v_lshl_add_u64 v[196:197], s[84:85], 0, v[216:217]
	s_add_i32 m0, s83, 0x2000
	v_lshl_add_u64 v[210:211], s[58:59], 0, v[218:219]
	global_load_lds_dwordx4 v[196:197], off
	s_mov_b32 m0, s67
	s_nop 0
	global_load_lds_dwordx4 v[208:209], off
	s_mov_b32 m0, s68
	s_nop 0
	global_load_lds_dwordx4 v[210:211], off
	s_waitcnt vmcnt(8)
	s_waitcnt lgkmcnt(0)
	s_barrier
	s_waitcnt lgkmcnt(0)
	v_mfma_f32_16x16x32_bf16 v[86:89], v[62:65], v[140:143], v[86:89]
	v_mfma_f32_16x16x32_bf16 v[54:57], v[70:73], v[140:143], v[54:57]
	v_mfma_f32_16x16x32_bf16 v[46:49], v[62:65], v[156:159], v[46:49]
	v_mfma_f32_16x16x32_bf16 v[38:41], v[70:73], v[156:159], v[38:41]
	v_mfma_f32_16x16x32_bf16 v[30:33], v[62:65], v[180:183], v[30:33]
	v_mfma_f32_16x16x32_bf16 v[22:25], v[70:73], v[180:183], v[22:25]
	v_mfma_f32_16x16x32_bf16 v[14:17], v[62:65], v[188:191], v[14:17]
	v_mfma_f32_16x16x32_bf16 v[6:9], v[70:73], v[188:191], v[6:9]
	v_mfma_f32_16x16x32_bf16 v[86:89], v[66:69], v[148:151], v[86:89]
	v_mfma_f32_16x16x32_bf16 v[54:57], v[74:77], v[148:151], v[54:57]
	v_mfma_f32_16x16x32_bf16 v[46:49], v[66:69], v[164:167], v[46:49]
	v_mfma_f32_16x16x32_bf16 v[38:41], v[74:77], v[164:167], v[38:41]
	v_mfma_f32_16x16x32_bf16 v[30:33], v[66:69], v[184:187], v[30:33]
	v_mfma_f32_16x16x32_bf16 v[22:25], v[74:77], v[184:187], v[22:25]
	v_mfma_f32_16x16x32_bf16 v[14:17], v[66:69], v[192:195], v[14:17]
	v_mfma_f32_16x16x32_bf16 v[6:9], v[74:77], v[192:195], v[6:9]
	v_mfma_f32_16x16x32_bf16 v[58:61], v[78:81], v[140:143], v[58:61]
	v_mfma_f32_16x16x32_bf16 v[50:53], v[90:93], v[140:143], v[50:53]
	v_mfma_f32_16x16x32_bf16 v[42:45], v[78:81], v[156:159], v[42:45]
	v_mfma_f32_16x16x32_bf16 v[34:37], v[90:93], v[156:159], v[34:37]
	v_mfma_f32_16x16x32_bf16 v[26:29], v[78:81], v[180:183], v[26:29]
	v_mfma_f32_16x16x32_bf16 v[18:21], v[90:93], v[180:183], v[18:21]
	v_mfma_f32_16x16x32_bf16 v[10:13], v[78:81], v[188:191], v[10:13]
	v_mfma_f32_16x16x32_bf16 v[2:5], v[90:93], v[188:191], v[2:5]
	v_mfma_f32_16x16x32_bf16 v[58:61], v[82:85], v[148:151], v[58:61]
	v_mfma_f32_16x16x32_bf16 v[50:53], v[94:97], v[148:151], v[50:53]
	v_mfma_f32_16x16x32_bf16 v[42:45], v[82:85], v[164:167], v[42:45]
	v_mfma_f32_16x16x32_bf16 v[34:37], v[94:97], v[164:167], v[34:37]
	v_mfma_f32_16x16x32_bf16 v[26:29], v[82:85], v[184:187], v[26:29]
	v_mfma_f32_16x16x32_bf16 v[18:21], v[94:97], v[184:187], v[18:21]
	v_mfma_f32_16x16x32_bf16 v[10:13], v[82:85], v[192:195], v[10:13]
	v_mfma_f32_16x16x32_bf16 v[2:5], v[94:97], v[192:195], v[2:5]
	s_barrier
	s_add_i32 s83, 0, 0x18000
	s_add_i32 s84, 0, 0x1c000
	v_add_u32_e32 v74, s83, v244
	v_add_u32_e32 v94, s84, v244
	ds_read_b128 v[62:65], v74
	ds_read_b128 v[66:69], v74 offset:1024
	ds_read_b128 v[70:73], v74 offset:2048
	ds_read_b128 v[74:77], v74 offset:3072
	ds_read_b128 v[78:81], v94
	ds_read_b128 v[82:85], v94 offset:1024
	ds_read_b128 v[90:93], v94 offset:2048
	ds_read_b128 v[94:97], v94 offset:3072
	s_add_u32 s58, s58, 0x100000
	s_addc_u32 s59, s59, 0
	s_mov_b32 m0, s69
	v_lshl_add_u64 v[156:157], s[58:59], 0, v[220:221]
	ds_read_b128 v[140:143], v250 offset:32768
	ds_read_b128 v[148:151], v250 offset:33792
	ds_read_b128 v[180:183], v250 offset:34816
	ds_read_b128 v[184:187], v250 offset:35840
	ds_read_b128 v[188:191], v250 offset:36864
	ds_read_b128 v[192:195], v250 offset:37888
	ds_read_b128 v[196:199], v250 offset:38912
	ds_read_b128 v[200:203], v250 offset:39936
	global_load_lds_dwordx4 v[156:157], off
	v_lshl_add_u64 v[156:157], s[58:59], 0, v[218:219]
	s_mov_b32 m0, s70
	s_nop 0
	global_load_lds_dwordx4 v[156:157], off
	s_waitcnt vmcnt(8)
	s_waitcnt lgkmcnt(0)
	s_barrier
	s_waitcnt lgkmcnt(0)
	v_mfma_f32_16x16x32_bf16 v[156:159], v[62:65], v[140:143], v[176:179]
	v_mfma_f32_16x16x32_bf16 v[176:179], v[66:69], v[148:151], v[156:159]
	v_mfma_f32_16x16x32_bf16 v[156:159], v[70:73], v[140:143], v[168:171]
	v_mfma_f32_16x16x32_bf16 v[168:171], v[74:77], v[148:151], v[156:159]
	v_mfma_f32_16x16x32_bf16 v[156:159], v[62:65], v[180:183], v[160:163]
	v_mfma_f32_16x16x32_bf16 v[152:155], v[70:73], v[180:183], v[152:155]
	v_mfma_f32_16x16x32_bf16 v[144:147], v[62:65], v[188:191], v[144:147]
	v_mfma_f32_16x16x32_bf16 v[136:139], v[70:73], v[188:191], v[136:139]
	v_mfma_f32_16x16x32_bf16 v[126:129], v[62:65], v[196:199], v[126:129]
	v_mfma_f32_16x16x32_bf16 v[118:121], v[70:73], v[196:199], v[118:121]
	v_mfma_f32_16x16x32_bf16 v[160:163], v[66:69], v[184:187], v[156:159]
	v_mfma_f32_16x16x32_bf16 v[152:155], v[74:77], v[184:187], v[152:155]
	v_mfma_f32_16x16x32_bf16 v[144:147], v[66:69], v[192:195], v[144:147]
	v_mfma_f32_16x16x32_bf16 v[136:139], v[74:77], v[192:195], v[136:139]
	v_mfma_f32_16x16x32_bf16 v[126:129], v[66:69], v[200:203], v[126:129]
	v_mfma_f32_16x16x32_bf16 v[118:121], v[74:77], v[200:203], v[118:121]
	v_mfma_f32_16x16x32_bf16 v[98:101], v[90:93], v[140:143], v[98:101]
	v_mfma_f32_16x16x32_bf16 v[156:159], v[78:81], v[140:143], v[172:175]
	v_mfma_f32_16x16x32_bf16 v[164:167], v[94:97], v[148:151], v[98:101]
	v_mfma_f32_16x16x32_bf16 v[98:101], v[78:81], v[180:183], v[102:105]
	v_mfma_f32_16x16x32_bf16 v[172:175], v[82:85], v[148:151], v[156:159]
	v_mfma_f32_16x16x32_bf16 v[156:159], v[82:85], v[184:187], v[98:101]
	v_mfma_f32_16x16x32_bf16 v[98:101], v[90:93], v[180:183], v[106:109]
	v_mfma_f32_16x16x32_bf16 v[148:151], v[94:97], v[184:187], v[98:101]
	v_mfma_f32_16x16x32_bf16 v[98:101], v[78:81], v[188:191], v[110:113]
	v_mfma_f32_16x16x32_bf16 v[140:143], v[82:85], v[192:195], v[98:101]
	v_mfma_f32_16x16x32_bf16 v[98:101], v[90:93], v[188:191], v[132:135]
	v_mfma_f32_16x16x32_bf16 v[132:135], v[94:97], v[192:195], v[98:101]
	v_mfma_f32_16x16x32_bf16 v[98:101], v[78:81], v[196:199], v[122:125]
	v_mfma_f32_16x16x32_bf16 v[122:125], v[82:85], v[200:203], v[98:101]
	v_mfma_f32_16x16x32_bf16 v[98:101], v[90:93], v[196:199], v[114:117]
	v_mfma_f32_16x16x32_bf16 v[114:117], v[94:97], v[200:203], v[98:101]
	s_barrier
	s_add_i32 s58, s83, s66
	v_lshl_add_u64 v[196:197], v[204:205], 0, s[18:19]
	s_mov_b32 m0, s58
	s_nop 1
	ds_read_b128 v[98:101], v250 offset:49152
	ds_read_b128 v[102:105], v250 offset:50176
	ds_read_b128 v[106:109], v250 offset:51200
	ds_read_b128 v[110:113], v250 offset:52224
	ds_read_b128 v[180:183], v250 offset:53248
	ds_read_b128 v[184:187], v250 offset:54272
	ds_read_b128 v[188:191], v250 offset:55296
	ds_read_b128 v[192:195], v250 offset:56320
	global_load_lds_dwordx4 v[196:197], off
	s_add_i32 m0, s58, 0x2000
	s_add_u32 s46, s46, 0x100080
	v_lshl_add_u64 v[196:197], v[206:207], 0, s[18:19]
	s_addc_u32 s47, s47, 0
	s_add_i32 s58, s84, s66
	global_load_lds_dwordx4 v[196:197], off
	v_lshl_add_u64 v[196:197], s[46:47], 0, v[130:131]
	s_mov_b32 m0, s58
	s_nop 0
	global_load_lds_dwordx4 v[196:197], off
	v_lshl_add_u64 v[196:197], s[46:47], 0, v[216:217]
	s_add_i32 m0, s58, 0x2000
	s_nop 0
	global_load_lds_dwordx4 v[196:197], off
	v_lshl_add_u64 v[196:197], v[208:209], 0, s[18:19]
	s_mov_b32 m0, s74
	s_nop 0
	global_load_lds_dwordx4 v[196:197], off
	v_lshl_add_u64 v[196:197], v[210:211], 0, s[18:19]
	s_mov_b32 m0, s75
	s_nop 0
	global_load_lds_dwordx4 v[196:197], off
	s_waitcnt vmcnt(8)
	s_waitcnt lgkmcnt(0)
	s_barrier
	s_waitcnt lgkmcnt(0)
	v_mfma_f32_16x16x32_bf16 v[86:89], v[62:65], v[98:101], v[86:89]
	v_mfma_f32_16x16x32_bf16 v[54:57], v[70:73], v[98:101], v[54:57]
	v_mfma_f32_16x16x32_bf16 v[46:49], v[62:65], v[106:109], v[46:49]
	v_mfma_f32_16x16x32_bf16 v[38:41], v[70:73], v[106:109], v[38:41]
	v_mfma_f32_16x16x32_bf16 v[30:33], v[62:65], v[180:183], v[30:33]
	v_mfma_f32_16x16x32_bf16 v[22:25], v[70:73], v[180:183], v[22:25]
	v_mfma_f32_16x16x32_bf16 v[14:17], v[62:65], v[188:191], v[14:17]
	v_mfma_f32_16x16x32_bf16 v[6:9], v[70:73], v[188:191], v[6:9]
	s_add_i32 s82, s82, 2
	v_mfma_f32_16x16x32_bf16 v[86:89], v[66:69], v[102:105], v[86:89]
	s_add_u32 s2, s2, 0x100
	v_mfma_f32_16x16x32_bf16 v[54:57], v[74:77], v[102:105], v[54:57]
	s_addc_u32 s3, s3, 0
	v_mfma_f32_16x16x32_bf16 v[46:49], v[66:69], v[110:113], v[46:49]
	s_add_u32 s80, s80, 0x100
	v_mfma_f32_16x16x32_bf16 v[38:41], v[74:77], v[110:113], v[38:41]
	s_addc_u32 s81, s81, 0
	v_mfma_f32_16x16x32_bf16 v[30:33], v[66:69], v[184:187], v[30:33]
	s_cmp_gt_u32 s82, 61
	v_mfma_f32_16x16x32_bf16 v[22:25], v[74:77], v[184:187], v[22:25]
	v_mfma_f32_16x16x32_bf16 v[14:17], v[66:69], v[192:195], v[14:17]
	v_mfma_f32_16x16x32_bf16 v[6:9], v[74:77], v[192:195], v[6:9]
	v_mfma_f32_16x16x32_bf16 v[58:61], v[78:81], v[98:101], v[58:61]
	v_mfma_f32_16x16x32_bf16 v[50:53], v[90:93], v[98:101], v[50:53]
	v_mfma_f32_16x16x32_bf16 v[42:45], v[78:81], v[106:109], v[42:45]
	v_mfma_f32_16x16x32_bf16 v[34:37], v[90:93], v[106:109], v[34:37]
	v_mfma_f32_16x16x32_bf16 v[26:29], v[78:81], v[180:183], v[26:29]
	v_mfma_f32_16x16x32_bf16 v[18:21], v[90:93], v[180:183], v[18:21]
	v_mfma_f32_16x16x32_bf16 v[10:13], v[78:81], v[188:191], v[10:13]
	v_mfma_f32_16x16x32_bf16 v[2:5], v[90:93], v[188:191], v[2:5]
	v_mfma_f32_16x16x32_bf16 v[58:61], v[82:85], v[102:105], v[58:61]
	v_mfma_f32_16x16x32_bf16 v[50:53], v[94:97], v[102:105], v[50:53]
	v_mfma_f32_16x16x32_bf16 v[42:45], v[82:85], v[110:113], v[42:45]
	v_mfma_f32_16x16x32_bf16 v[34:37], v[94:97], v[110:113], v[34:37]
	v_mfma_f32_16x16x32_bf16 v[26:29], v[82:85], v[184:187], v[26:29]
	v_mfma_f32_16x16x32_bf16 v[18:21], v[94:97], v[184:187], v[18:21]
	v_mfma_f32_16x16x32_bf16 v[10:13], v[82:85], v[192:195], v[10:13]
	v_mfma_f32_16x16x32_bf16 v[2:5], v[94:97], v[192:195], v[2:5]
	s_barrier
	s_cbranch_scc0 .LBB0_1024
	v_mov_b64_e32 v[214:215], 0x400
	s_and_b64 vcc, exec, s[16:17]
	s_cbranch_vccz .LBB0_1027
	s_barrier

.LBB0_1328:
	s_add_u32 s24, s22, 0x100
	s_addc_u32 s25, s23, 0
	s_add_i32 s57, 0, 0x10000
	s_cmpk_eq_i32 s56, 0xa8
	s_cselect_b32 s29, s3, s25
	s_cselect_b32 s28, s2, s24
	v_add_u32_e32 v146, s57, v149
	s_cselect_b32 s27, s17, s55
	s_cselect_b32 s26, s16, s54
	s_add_i32 s58, 0, 0x14000
	ds_read_b128 v[142:145], v146
	ds_read_b128 v[152:155], v146 offset:1024
	ds_read_b128 v[156:159], v146 offset:2048
	ds_read_b128 v[160:163], v146 offset:3072
	v_add_u32_e32 v146, s58, v149
	ds_read_b128 v[164:167], v146
	ds_read_b128 v[168:171], v146 offset:1024
	ds_read_b128 v[172:175], v146 offset:2048
	ds_read_b128 v[176:179], v146 offset:3072
	v_lshl_add_u64 v[146:147], s[22:23], 0, v[138:139]
	s_add_i32 m0, s41, 0xc000
	ds_read_b128 v[180:183], v151
	ds_read_b128 v[184:187], v151 offset:1024
	ds_read_b128 v[188:191], v151 offset:2048
	ds_read_b128 v[192:195], v151 offset:3072
	ds_read_b128 v[196:199], v151 offset:4096
	ds_read_b128 v[200:203], v151 offset:5120
	ds_read_b128 v[204:207], v151 offset:6144
	ds_read_b128 v[208:211], v151 offset:7168
	global_load_lds_dwordx4 v[146:147], off
	v_lshl_add_u64 v[146:147], s[22:23], 0, v[140:141]
	s_add_i32 m0, s41, 0xe000
	s_nop 0
	global_load_lds_dwordx4 v[146:147], off
	s_waitcnt vmcnt(8)
	s_waitcnt lgkmcnt(0)
	s_barrier
	s_waitcnt lgkmcnt(0)
	v_mfma_f32_16x16x32_bf16 v[126:129], v[142:145], v[180:183], v[126:129]
	v_mfma_f32_16x16x32_bf16 v[122:125], v[156:159], v[180:183], v[122:125]
	v_mfma_f32_16x16x32_bf16 v[110:113], v[142:145], v[188:191], v[110:113]
	v_mfma_f32_16x16x32_bf16 v[106:109], v[156:159], v[188:191], v[106:109]
	v_mfma_f32_16x16x32_bf16 v[94:97], v[142:145], v[196:199], v[94:97]
	v_mfma_f32_16x16x32_bf16 v[90:93], v[156:159], v[196:199], v[90:93]
	v_mfma_f32_16x16x32_bf16 v[78:81], v[142:145], v[204:207], v[78:81]
	v_mfma_f32_16x16x32_bf16 v[74:77], v[156:159], v[204:207], v[74:77]
	v_mfma_f32_16x16x32_bf16 v[126:129], v[152:155], v[184:187], v[126:129]
	v_mfma_f32_16x16x32_bf16 v[122:125], v[160:163], v[184:187], v[122:125]
	v_mfma_f32_16x16x32_bf16 v[110:113], v[152:155], v[192:195], v[110:113]
	v_mfma_f32_16x16x32_bf16 v[106:109], v[160:163], v[192:195], v[106:109]
	v_mfma_f32_16x16x32_bf16 v[94:97], v[152:155], v[200:203], v[94:97]
	v_mfma_f32_16x16x32_bf16 v[90:93], v[160:163], v[200:203], v[90:93]
	v_mfma_f32_16x16x32_bf16 v[78:81], v[152:155], v[208:211], v[78:81]
	v_mfma_f32_16x16x32_bf16 v[74:77], v[160:163], v[208:211], v[74:77]
	v_mfma_f32_16x16x32_bf16 v[118:121], v[164:167], v[180:183], v[118:121]
	v_mfma_f32_16x16x32_bf16 v[114:117], v[172:175], v[180:183], v[114:117]
	v_mfma_f32_16x16x32_bf16 v[102:105], v[164:167], v[188:191], v[102:105]
	v_mfma_f32_16x16x32_bf16 v[98:101], v[172:175], v[188:191], v[98:101]
	v_mfma_f32_16x16x32_bf16 v[86:89], v[164:167], v[196:199], v[86:89]
	v_mfma_f32_16x16x32_bf16 v[82:85], v[172:175], v[196:199], v[82:85]
	v_mfma_f32_16x16x32_bf16 v[70:73], v[164:167], v[204:207], v[70:73]
	v_mfma_f32_16x16x32_bf16 v[66:69], v[172:175], v[204:207], v[66:69]
	v_mfma_f32_16x16x32_bf16 v[118:121], v[168:171], v[184:187], v[118:121]
	v_mfma_f32_16x16x32_bf16 v[114:117], v[176:179], v[184:187], v[114:117]
	v_mfma_f32_16x16x32_bf16 v[102:105], v[168:171], v[192:195], v[102:105]
	v_mfma_f32_16x16x32_bf16 v[98:101], v[176:179], v[192:195], v[98:101]
	v_mfma_f32_16x16x32_bf16 v[86:89], v[168:171], v[200:203], v[86:89]
	v_mfma_f32_16x16x32_bf16 v[82:85], v[176:179], v[200:203], v[82:85]
	v_mfma_f32_16x16x32_bf16 v[70:73], v[168:171], v[208:211], v[70:73]
	v_mfma_f32_16x16x32_bf16 v[66:69], v[176:179], v[208:211], v[66:69]
	s_barrier
	s_add_i32 s22, s57, s40
	v_lshl_add_u64 v[146:147], s[26:27], 0, v[130:131]
	s_mov_b32 m0, s22
	ds_read_b128 v[180:183], v151 offset:16384
	ds_read_b128 v[184:187], v151 offset:17408
	ds_read_b128 v[188:191], v151 offset:18432
	ds_read_b128 v[192:195], v151 offset:19456
	ds_read_b128 v[196:199], v151 offset:20480
	ds_read_b128 v[200:203], v151 offset:21504
	ds_read_b128 v[204:207], v151 offset:22528
	ds_read_b128 v[208:211], v151 offset:23552
	global_load_lds_dwordx4 v[146:147], off
	s_add_i32 m0, s22, 0x2000
	s_add_u32 s22, s26, 0x2b0000
	v_lshl_add_u64 v[212:213], s[26:27], 0, v[132:133]
	s_addc_u32 s23, s27, 0
	s_add_i32 s57, s58, s40
	global_load_lds_dwordx4 v[212:213], off
	v_lshl_add_u64 v[216:217], s[22:23], 0, v[130:131]
	s_mov_b32 m0, s57
	v_lshl_add_u64 v[218:219], s[28:29], 0, v[134:135]
	global_load_lds_dwordx4 v[216:217], off
	v_lshl_add_u64 v[216:217], s[22:23], 0, v[132:133]
	s_add_i32 m0, s57, 0x2000
	s_nop 0
	global_load_lds_dwordx4 v[216:217], off
	v_lshl_add_u64 v[216:217], s[28:29], 0, v[136:137]
	s_mov_b32 m0, s41
	s_nop 0
	global_load_lds_dwordx4 v[216:217], off
	s_mov_b32 m0, s44
	s_nop 0
	global_load_lds_dwordx4 v[218:219], off
	s_waitcnt vmcnt(8)
	s_waitcnt lgkmcnt(0)
	s_barrier
	s_waitcnt lgkmcnt(0)
	v_mfma_f32_16x16x32_bf16 v[62:65], v[142:145], v[180:183], v[62:65]
	v_mfma_f32_16x16x32_bf16 v[58:61], v[156:159], v[180:183], v[58:61]
	v_mfma_f32_16x16x32_bf16 v[46:49], v[142:145], v[188:191], v[46:49]
	v_mfma_f32_16x16x32_bf16 v[42:45], v[156:159], v[188:191], v[42:45]
	v_mfma_f32_16x16x32_bf16 v[30:33], v[142:145], v[196:199], v[30:33]
	v_mfma_f32_16x16x32_bf16 v[26:29], v[156:159], v[196:199], v[26:29]
	v_mfma_f32_16x16x32_bf16 v[14:17], v[142:145], v[204:207], v[14:17]
	v_mfma_f32_16x16x32_bf16 v[10:13], v[156:159], v[204:207], v[10:13]
	v_mfma_f32_16x16x32_bf16 v[62:65], v[152:155], v[184:187], v[62:65]
	v_mfma_f32_16x16x32_bf16 v[58:61], v[160:163], v[184:187], v[58:61]
	v_mfma_f32_16x16x32_bf16 v[46:49], v[152:155], v[192:195], v[46:49]
	v_mfma_f32_16x16x32_bf16 v[42:45], v[160:163], v[192:195], v[42:45]
	v_mfma_f32_16x16x32_bf16 v[30:33], v[152:155], v[200:203], v[30:33]
	v_mfma_f32_16x16x32_bf16 v[26:29], v[160:163], v[200:203], v[26:29]
	v_mfma_f32_16x16x32_bf16 v[14:17], v[152:155], v[208:211], v[14:17]
	v_mfma_f32_16x16x32_bf16 v[10:13], v[160:163], v[208:211], v[10:13]
	v_mfma_f32_16x16x32_bf16 v[54:57], v[164:167], v[180:183], v[54:57]
	v_mfma_f32_16x16x32_bf16 v[50:53], v[172:175], v[180:183], v[50:53]
	v_mfma_f32_16x16x32_bf16 v[38:41], v[164:167], v[188:191], v[38:41]
	v_mfma_f32_16x16x32_bf16 v[34:37], v[172:175], v[188:191], v[34:37]
	v_mfma_f32_16x16x32_bf16 v[22:25], v[164:167], v[196:199], v[22:25]
	v_mfma_f32_16x16x32_bf16 v[18:21], v[172:175], v[196:199], v[18:21]
	v_mfma_f32_16x16x32_bf16 v[6:9], v[164:167], v[204:207], v[6:9]
	v_mfma_f32_16x16x32_bf16 v[2:5], v[172:175], v[204:207], v[2:5]
	v_mfma_f32_16x16x32_bf16 v[54:57], v[168:171], v[184:187], v[54:57]
	v_mfma_f32_16x16x32_bf16 v[50:53], v[176:179], v[184:187], v[50:53]
	v_mfma_f32_16x16x32_bf16 v[38:41], v[168:171], v[192:195], v[38:41]
	v_mfma_f32_16x16x32_bf16 v[34:37], v[176:179], v[192:195], v[34:37]
	v_mfma_f32_16x16x32_bf16 v[22:25], v[168:171], v[200:203], v[22:25]
	v_mfma_f32_16x16x32_bf16 v[18:21], v[176:179], v[200:203], v[18:21]
	v_mfma_f32_16x16x32_bf16 v[6:9], v[168:171], v[208:211], v[6:9]
	v_mfma_f32_16x16x32_bf16 v[2:5], v[176:179], v[208:211], v[2:5]
	s_barrier
	s_add_i32 s57, 0, 0x18000
	s_add_i32 s58, 0, 0x1c000
	v_add_u32_e32 v160, s57, v149
	v_add_u32_e32 v176, s58, v149
	ds_read_b128 v[142:145], v160
	ds_read_b128 v[152:155], v160 offset:1024
	ds_read_b128 v[156:159], v160 offset:2048
	ds_read_b128 v[160:163], v160 offset:3072
	ds_read_b128 v[164:167], v176
	ds_read_b128 v[168:171], v176 offset:1024
	ds_read_b128 v[172:175], v176 offset:2048
	ds_read_b128 v[176:179], v176 offset:3072
	s_add_u32 s22, s28, 0x2b0000
	s_addc_u32 s23, s29, 0
	s_mov_b32 m0, s45
	v_lshl_add_u64 v[220:221], s[22:23], 0, v[136:137]
	ds_read_b128 v[180:183], v151 offset:32768
	ds_read_b128 v[184:187], v151 offset:33792
	ds_read_b128 v[188:191], v151 offset:34816
	ds_read_b128 v[192:195], v151 offset:35840
	ds_read_b128 v[196:199], v151 offset:36864
	ds_read_b128 v[200:203], v151 offset:37888
	ds_read_b128 v[204:207], v151 offset:38912
	ds_read_b128 v[208:211], v151 offset:39936
	global_load_lds_dwordx4 v[220:221], off
	v_lshl_add_u64 v[220:221], s[22:23], 0, v[134:135]
	s_mov_b32 m0, s46
	s_nop 0
	global_load_lds_dwordx4 v[220:221], off
	s_waitcnt vmcnt(8)
	s_waitcnt lgkmcnt(0)
	s_barrier
	s_waitcnt lgkmcnt(0)
	v_mfma_f32_16x16x32_bf16 v[126:129], v[142:145], v[180:183], v[126:129]
	v_mfma_f32_16x16x32_bf16 v[122:125], v[156:159], v[180:183], v[122:125]
	v_mfma_f32_16x16x32_bf16 v[110:113], v[142:145], v[188:191], v[110:113]
	v_mfma_f32_16x16x32_bf16 v[106:109], v[156:159], v[188:191], v[106:109]
	v_mfma_f32_16x16x32_bf16 v[94:97], v[142:145], v[196:199], v[94:97]
	v_mfma_f32_16x16x32_bf16 v[90:93], v[156:159], v[196:199], v[90:93]
	v_mfma_f32_16x16x32_bf16 v[78:81], v[142:145], v[204:207], v[78:81]
	v_mfma_f32_16x16x32_bf16 v[74:77], v[156:159], v[204:207], v[74:77]
	v_mfma_f32_16x16x32_bf16 v[126:129], v[152:155], v[184:187], v[126:129]
	v_mfma_f32_16x16x32_bf16 v[122:125], v[160:163], v[184:187], v[122:125]
	v_mfma_f32_16x16x32_bf16 v[110:113], v[152:155], v[192:195], v[110:113]
	v_mfma_f32_16x16x32_bf16 v[106:109], v[160:163], v[192:195], v[106:109]
	v_mfma_f32_16x16x32_bf16 v[94:97], v[152:155], v[200:203], v[94:97]
	v_mfma_f32_16x16x32_bf16 v[90:93], v[160:163], v[200:203], v[90:93]
	v_mfma_f32_16x16x32_bf16 v[78:81], v[152:155], v[208:211], v[78:81]
	v_mfma_f32_16x16x32_bf16 v[74:77], v[160:163], v[208:211], v[74:77]
	v_mfma_f32_16x16x32_bf16 v[118:121], v[164:167], v[180:183], v[118:121]
	v_mfma_f32_16x16x32_bf16 v[114:117], v[172:175], v[180:183], v[114:117]
	v_mfma_f32_16x16x32_bf16 v[102:105], v[164:167], v[188:191], v[102:105]
	v_mfma_f32_16x16x32_bf16 v[98:101], v[172:175], v[188:191], v[98:101]
	v_mfma_f32_16x16x32_bf16 v[86:89], v[164:167], v[196:199], v[86:89]
	v_mfma_f32_16x16x32_bf16 v[82:85], v[172:175], v[196:199], v[82:85]
	v_mfma_f32_16x16x32_bf16 v[70:73], v[164:167], v[204:207], v[70:73]
	v_mfma_f32_16x16x32_bf16 v[66:69], v[172:175], v[204:207], v[66:69]
	v_mfma_f32_16x16x32_bf16 v[118:121], v[168:171], v[184:187], v[118:121]
	v_mfma_f32_16x16x32_bf16 v[114:117], v[176:179], v[184:187], v[114:117]
	v_mfma_f32_16x16x32_bf16 v[102:105], v[168:171], v[192:195], v[102:105]
	v_mfma_f32_16x16x32_bf16 v[98:101], v[176:179], v[192:195], v[98:101]
	v_mfma_f32_16x16x32_bf16 v[86:89], v[168:171], v[200:203], v[86:89]
	v_mfma_f32_16x16x32_bf16 v[82:85], v[176:179], v[200:203], v[82:85]
	v_mfma_f32_16x16x32_bf16 v[70:73], v[168:171], v[208:211], v[70:73]
	v_mfma_f32_16x16x32_bf16 v[66:69], v[176:179], v[208:211], v[66:69]
	s_barrier
	s_add_i32 s22, s57, s40
	v_lshl_add_u64 v[146:147], v[146:147], 0, s[18:19]
	s_mov_b32 m0, s22
	ds_read_b128 v[180:183], v151 offset:49152
	ds_read_b128 v[184:187], v151 offset:50176
	ds_read_b128 v[188:191], v151 offset:51200
	ds_read_b128 v[192:195], v151 offset:52224
	ds_read_b128 v[196:199], v151 offset:53248
	ds_read_b128 v[200:203], v151 offset:54272
	ds_read_b128 v[204:207], v151 offset:55296
	ds_read_b128 v[208:211], v151 offset:56320
	global_load_lds_dwordx4 v[146:147], off
	s_add_i32 m0, s22, 0x2000
	s_add_u32 s22, s26, 0x2b0080
	v_lshl_add_u64 v[146:147], v[212:213], 0, s[18:19]
	s_addc_u32 s23, s27, 0
	s_add_i32 s26, s58, s40
	global_load_lds_dwordx4 v[146:147], off
	v_lshl_add_u64 v[146:147], s[22:23], 0, v[130:131]
	s_mov_b32 m0, s26
	s_nop 0
	global_load_lds_dwordx4 v[146:147], off
	v_lshl_add_u64 v[146:147], s[22:23], 0, v[132:133]
	s_add_i32 m0, s26, 0x2000
	s_nop 0
	global_load_lds_dwordx4 v[146:147], off
	v_lshl_add_u64 v[146:147], v[216:217], 0, s[18:19]
	s_mov_b32 m0, s47
	s_nop 0
	global_load_lds_dwordx4 v[146:147], off
	v_lshl_add_u64 v[146:147], v[218:219], 0, s[18:19]
	s_mov_b32 m0, s48
	s_nop 0
	global_load_lds_dwordx4 v[146:147], off
	s_waitcnt vmcnt(8)
	s_waitcnt lgkmcnt(0)
	s_barrier
	s_waitcnt lgkmcnt(0)
	v_mfma_f32_16x16x32_bf16 v[62:65], v[142:145], v[180:183], v[62:65]
	v_mfma_f32_16x16x32_bf16 v[58:61], v[156:159], v[180:183], v[58:61]
	v_mfma_f32_16x16x32_bf16 v[46:49], v[142:145], v[188:191], v[46:49]
	v_mfma_f32_16x16x32_bf16 v[42:45], v[156:159], v[188:191], v[42:45]
	v_mfma_f32_16x16x32_bf16 v[30:33], v[142:145], v[196:199], v[30:33]
	v_mfma_f32_16x16x32_bf16 v[26:29], v[156:159], v[196:199], v[26:29]
	v_mfma_f32_16x16x32_bf16 v[14:17], v[142:145], v[204:207], v[14:17]
	v_mfma_f32_16x16x32_bf16 v[10:13], v[156:159], v[204:207], v[10:13]
	s_add_i32 s56, s56, 2
	v_mfma_f32_16x16x32_bf16 v[62:65], v[152:155], v[184:187], v[62:65]
	s_add_u32 s54, s54, 0x100
	v_mfma_f32_16x16x32_bf16 v[58:61], v[160:163], v[184:187], v[58:61]
	s_addc_u32 s55, s55, 0
	v_mfma_f32_16x16x32_bf16 v[46:49], v[152:155], v[192:195], v[46:49]
	s_cmpk_gt_u32 s56, 0xa9
	v_mfma_f32_16x16x32_bf16 v[42:45], v[160:163], v[192:195], v[42:45]
	s_mov_b64 s[22:23], s[24:25]
	v_mfma_f32_16x16x32_bf16 v[30:33], v[152:155], v[200:203], v[30:33]
	v_mfma_f32_16x16x32_bf16 v[26:29], v[160:163], v[200:203], v[26:29]
	v_mfma_f32_16x16x32_bf16 v[14:17], v[152:155], v[208:211], v[14:17]
	v_mfma_f32_16x16x32_bf16 v[10:13], v[160:163], v[208:211], v[10:13]
	v_mfma_f32_16x16x32_bf16 v[54:57], v[164:167], v[180:183], v[54:57]
	v_mfma_f32_16x16x32_bf16 v[50:53], v[172:175], v[180:183], v[50:53]
	v_mfma_f32_16x16x32_bf16 v[38:41], v[164:167], v[188:191], v[38:41]
	v_mfma_f32_16x16x32_bf16 v[34:37], v[172:175], v[188:191], v[34:37]
	v_mfma_f32_16x16x32_bf16 v[22:25], v[164:167], v[196:199], v[22:25]
	v_mfma_f32_16x16x32_bf16 v[18:21], v[172:175], v[196:199], v[18:21]
	v_mfma_f32_16x16x32_bf16 v[6:9], v[164:167], v[204:207], v[6:9]
	v_mfma_f32_16x16x32_bf16 v[2:5], v[172:175], v[204:207], v[2:5]
	v_mfma_f32_16x16x32_bf16 v[54:57], v[168:171], v[184:187], v[54:57]
	v_mfma_f32_16x16x32_bf16 v[50:53], v[176:179], v[184:187], v[50:53]
	v_mfma_f32_16x16x32_bf16 v[38:41], v[168:171], v[192:195], v[38:41]
	v_mfma_f32_16x16x32_bf16 v[34:37], v[176:179], v[192:195], v[34:37]
	v_mfma_f32_16x16x32_bf16 v[22:25], v[168:171], v[200:203], v[22:25]
	v_mfma_f32_16x16x32_bf16 v[18:21], v[176:179], v[200:203], v[18:21]
	v_mfma_f32_16x16x32_bf16 v[6:9], v[168:171], v[208:211], v[6:9]
	v_mfma_f32_16x16x32_bf16 v[2:5], v[176:179], v[208:211], v[2:5]
	s_barrier
	s_cbranch_scc0 .LBB0_1328
	s_and_b64 vcc, exec, s[12:13]
	s_cbranch_vccz .LBB0_1331
	s_barrier

.LBB0_1354:
	s_add_u32 s24, s22, 0x100
	s_addc_u32 s25, s23, 0
	s_add_i32 s60, 0, 0x10000
	s_cmpk_eq_i32 s59, 0xa8
	s_cselect_b32 s29, s3, s25
	s_cselect_b32 s28, s2, s24
	v_add_u32_e32 v149, s60, v194
	s_cselect_b32 s27, s13, s58
	s_cselect_b32 s26, s12, s57
	s_add_i32 s61, 0, 0x14000
	ds_read_b128 v[132:135], v149
	ds_read_b128 v[150:153], v149 offset:1024
	ds_read_b128 v[154:157], v149 offset:2048
	ds_read_b128 v[158:161], v149 offset:3072
	v_add_u32_e32 v149, s61, v194
	ds_read_b128 v[162:165], v149
	ds_read_b128 v[166:169], v149 offset:1024
	ds_read_b128 v[170:173], v149 offset:2048
	ds_read_b128 v[174:177], v149 offset:3072
	v_lshl_add_u64 v[190:191], s[22:23], 0, v[144:145]
	s_add_i32 m0, s48, 0xc000
	ds_read_b128 v[178:181], v196
	ds_read_b128 v[182:185], v196 offset:1024
	ds_read_b128 v[186:189], v196 offset:2048
	ds_read_b128 v[198:201], v196 offset:3072
	ds_read_b128 v[202:205], v196 offset:4096
	ds_read_b128 v[206:209], v196 offset:5120
	ds_read_b128 v[210:213], v196 offset:6144
	ds_read_b128 v[216:219], v196 offset:7168
	global_load_lds_dwordx4 v[190:191], off
	v_lshl_add_u64 v[190:191], s[22:23], 0, v[146:147]
	s_add_i32 m0, s48, 0xe000
	s_nop 0
	global_load_lds_dwordx4 v[190:191], off
	s_waitcnt vmcnt(8)
	s_waitcnt lgkmcnt(0)
	s_barrier
	s_waitcnt lgkmcnt(0)
	v_mfma_f32_16x16x32_bf16 v[126:129], v[132:135], v[178:181], v[126:129]
	v_mfma_f32_16x16x32_bf16 v[122:125], v[154:157], v[178:181], v[122:125]
	v_mfma_f32_16x16x32_bf16 v[110:113], v[132:135], v[186:189], v[110:113]
	v_mfma_f32_16x16x32_bf16 v[106:109], v[154:157], v[186:189], v[106:109]
	v_mfma_f32_16x16x32_bf16 v[94:97], v[132:135], v[202:205], v[94:97]
	v_mfma_f32_16x16x32_bf16 v[90:93], v[154:157], v[202:205], v[90:93]
	v_mfma_f32_16x16x32_bf16 v[78:81], v[132:135], v[210:213], v[78:81]
	v_mfma_f32_16x16x32_bf16 v[74:77], v[154:157], v[210:213], v[74:77]
	v_mfma_f32_16x16x32_bf16 v[126:129], v[150:153], v[182:185], v[126:129]
	v_mfma_f32_16x16x32_bf16 v[122:125], v[158:161], v[182:185], v[122:125]
	v_mfma_f32_16x16x32_bf16 v[110:113], v[150:153], v[198:201], v[110:113]
	v_mfma_f32_16x16x32_bf16 v[106:109], v[158:161], v[198:201], v[106:109]
	v_mfma_f32_16x16x32_bf16 v[94:97], v[150:153], v[206:209], v[94:97]
	v_mfma_f32_16x16x32_bf16 v[90:93], v[158:161], v[206:209], v[90:93]
	v_mfma_f32_16x16x32_bf16 v[78:81], v[150:153], v[216:219], v[78:81]
	v_mfma_f32_16x16x32_bf16 v[74:77], v[158:161], v[216:219], v[74:77]
	v_mfma_f32_16x16x32_bf16 v[118:121], v[162:165], v[178:181], v[118:121]
	v_mfma_f32_16x16x32_bf16 v[114:117], v[170:173], v[178:181], v[114:117]
	v_mfma_f32_16x16x32_bf16 v[102:105], v[162:165], v[186:189], v[102:105]
	v_mfma_f32_16x16x32_bf16 v[98:101], v[170:173], v[186:189], v[98:101]
	v_mfma_f32_16x16x32_bf16 v[86:89], v[162:165], v[202:205], v[86:89]
	v_mfma_f32_16x16x32_bf16 v[82:85], v[170:173], v[202:205], v[82:85]
	v_mfma_f32_16x16x32_bf16 v[70:73], v[162:165], v[210:213], v[70:73]
	v_mfma_f32_16x16x32_bf16 v[66:69], v[170:173], v[210:213], v[66:69]
	v_mfma_f32_16x16x32_bf16 v[118:121], v[166:169], v[182:185], v[118:121]
	v_mfma_f32_16x16x32_bf16 v[114:117], v[174:177], v[182:185], v[114:117]
	v_mfma_f32_16x16x32_bf16 v[102:105], v[166:169], v[198:201], v[102:105]
	v_mfma_f32_16x16x32_bf16 v[98:101], v[174:177], v[198:201], v[98:101]
	v_mfma_f32_16x16x32_bf16 v[86:89], v[166:169], v[206:209], v[86:89]
	v_mfma_f32_16x16x32_bf16 v[82:85], v[174:177], v[206:209], v[82:85]
	v_mfma_f32_16x16x32_bf16 v[70:73], v[166:169], v[216:219], v[70:73]
	v_mfma_f32_16x16x32_bf16 v[66:69], v[174:177], v[216:219], v[66:69]
	s_barrier
	s_add_i32 s22, s60, s30
	v_lshl_add_u64 v[190:191], s[26:27], 0, v[140:141]
	s_mov_b32 m0, s22
	ds_read_b128 v[178:181], v196 offset:16384
	ds_read_b128 v[182:185], v196 offset:17408
	ds_read_b128 v[186:189], v196 offset:18432
	ds_read_b128 v[198:201], v196 offset:19456
	ds_read_b128 v[202:205], v196 offset:20480
	ds_read_b128 v[206:209], v196 offset:21504
	ds_read_b128 v[210:213], v196 offset:22528
	ds_read_b128 v[216:219], v196 offset:23552
	global_load_lds_dwordx4 v[190:191], off
	s_add_i32 m0, s22, 0x2000
	s_add_u32 s22, s26, 0x2b0000
	v_lshl_add_u64 v[220:221], s[26:27], 0, v[136:137]
	s_addc_u32 s23, s27, 0
	s_add_i32 s60, s61, s30
	global_load_lds_dwordx4 v[220:221], off
	v_lshl_add_u64 v[222:223], s[22:23], 0, v[140:141]
	s_mov_b32 m0, s60
	v_lshl_add_u64 v[224:225], s[28:29], 0, v[138:139]
	global_load_lds_dwordx4 v[222:223], off
	v_lshl_add_u64 v[222:223], s[22:23], 0, v[136:137]
	s_add_i32 m0, s60, 0x2000
	s_nop 0
	global_load_lds_dwordx4 v[222:223], off
	v_lshl_add_u64 v[222:223], s[28:29], 0, v[142:143]
	s_mov_b32 m0, s48
	s_nop 0
	global_load_lds_dwordx4 v[222:223], off
	s_mov_b32 m0, s49
	s_nop 0
	global_load_lds_dwordx4 v[224:225], off
	s_waitcnt vmcnt(8)
	s_waitcnt lgkmcnt(0)
	s_barrier
	s_waitcnt lgkmcnt(0)
	v_mfma_f32_16x16x32_bf16 v[62:65], v[132:135], v[178:181], v[62:65]
	v_mfma_f32_16x16x32_bf16 v[58:61], v[154:157], v[178:181], v[58:61]
	v_mfma_f32_16x16x32_bf16 v[46:49], v[132:135], v[186:189], v[46:49]
	v_mfma_f32_16x16x32_bf16 v[42:45], v[154:157], v[186:189], v[42:45]
	v_mfma_f32_16x16x32_bf16 v[30:33], v[132:135], v[202:205], v[30:33]
	v_mfma_f32_16x16x32_bf16 v[26:29], v[154:157], v[202:205], v[26:29]
	v_mfma_f32_16x16x32_bf16 v[14:17], v[132:135], v[210:213], v[14:17]
	v_mfma_f32_16x16x32_bf16 v[10:13], v[154:157], v[210:213], v[10:13]
	v_mfma_f32_16x16x32_bf16 v[62:65], v[150:153], v[182:185], v[62:65]
	v_mfma_f32_16x16x32_bf16 v[58:61], v[158:161], v[182:185], v[58:61]
	v_mfma_f32_16x16x32_bf16 v[46:49], v[150:153], v[198:201], v[46:49]
	v_mfma_f32_16x16x32_bf16 v[42:45], v[158:161], v[198:201], v[42:45]
	v_mfma_f32_16x16x32_bf16 v[30:33], v[150:153], v[206:209], v[30:33]
	v_mfma_f32_16x16x32_bf16 v[26:29], v[158:161], v[206:209], v[26:29]
	v_mfma_f32_16x16x32_bf16 v[14:17], v[150:153], v[216:219], v[14:17]
	v_mfma_f32_16x16x32_bf16 v[10:13], v[158:161], v[216:219], v[10:13]
	v_mfma_f32_16x16x32_bf16 v[54:57], v[162:165], v[178:181], v[54:57]
	v_mfma_f32_16x16x32_bf16 v[50:53], v[170:173], v[178:181], v[50:53]
	v_mfma_f32_16x16x32_bf16 v[38:41], v[162:165], v[186:189], v[38:41]
	v_mfma_f32_16x16x32_bf16 v[34:37], v[170:173], v[186:189], v[34:37]
	v_mfma_f32_16x16x32_bf16 v[22:25], v[162:165], v[202:205], v[22:25]
	v_mfma_f32_16x16x32_bf16 v[18:21], v[170:173], v[202:205], v[18:21]
	v_mfma_f32_16x16x32_bf16 v[6:9], v[162:165], v[210:213], v[6:9]
	v_mfma_f32_16x16x32_bf16 v[2:5], v[170:173], v[210:213], v[2:5]
	v_mfma_f32_16x16x32_bf16 v[54:57], v[166:169], v[182:185], v[54:57]
	v_mfma_f32_16x16x32_bf16 v[50:53], v[174:177], v[182:185], v[50:53]
	v_mfma_f32_16x16x32_bf16 v[38:41], v[166:169], v[198:201], v[38:41]
	v_mfma_f32_16x16x32_bf16 v[34:37], v[174:177], v[198:201], v[34:37]
	v_mfma_f32_16x16x32_bf16 v[22:25], v[166:169], v[206:209], v[22:25]
	v_mfma_f32_16x16x32_bf16 v[18:21], v[174:177], v[206:209], v[18:21]
	v_mfma_f32_16x16x32_bf16 v[6:9], v[166:169], v[216:219], v[6:9]
	v_mfma_f32_16x16x32_bf16 v[2:5], v[174:177], v[216:219], v[2:5]
	s_barrier
	s_add_i32 s60, 0, 0x18000
	v_add_u32_e32 v149, s60, v194
	s_add_i32 s61, 0, 0x1c000
	ds_read_b128 v[132:135], v149
	ds_read_b128 v[150:153], v149 offset:1024
	ds_read_b128 v[154:157], v149 offset:2048
	ds_read_b128 v[158:161], v149 offset:3072
	v_add_u32_e32 v149, s61, v194
	ds_read_b128 v[162:165], v149
	ds_read_b128 v[166:169], v149 offset:1024
	ds_read_b128 v[170:173], v149 offset:2048
	ds_read_b128 v[174:177], v149 offset:3072
	s_add_u32 s22, s28, 0x2b0000
	s_addc_u32 s23, s29, 0
	s_mov_b32 m0, s50
	v_lshl_add_u64 v[226:227], s[22:23], 0, v[142:143]
	ds_read_b128 v[178:181], v196 offset:32768
	ds_read_b128 v[182:185], v196 offset:33792
	ds_read_b128 v[186:189], v196 offset:34816
	ds_read_b128 v[198:201], v196 offset:35840
	ds_read_b128 v[202:205], v196 offset:36864
	ds_read_b128 v[206:209], v196 offset:37888
	ds_read_b128 v[210:213], v196 offset:38912
	ds_read_b128 v[216:219], v196 offset:39936
	global_load_lds_dwordx4 v[226:227], off
	v_lshl_add_u64 v[226:227], s[22:23], 0, v[138:139]
	s_mov_b32 m0, s51
	s_nop 0
	global_load_lds_dwordx4 v[226:227], off
	s_waitcnt vmcnt(8)
	s_waitcnt lgkmcnt(0)
	s_barrier
	s_waitcnt lgkmcnt(0)
	v_mfma_f32_16x16x32_bf16 v[126:129], v[132:135], v[178:181], v[126:129]
	v_mfma_f32_16x16x32_bf16 v[122:125], v[154:157], v[178:181], v[122:125]
	v_mfma_f32_16x16x32_bf16 v[110:113], v[132:135], v[186:189], v[110:113]
	v_mfma_f32_16x16x32_bf16 v[106:109], v[154:157], v[186:189], v[106:109]
	v_mfma_f32_16x16x32_bf16 v[94:97], v[132:135], v[202:205], v[94:97]
	v_mfma_f32_16x16x32_bf16 v[90:93], v[154:157], v[202:205], v[90:93]
	v_mfma_f32_16x16x32_bf16 v[78:81], v[132:135], v[210:213], v[78:81]
	v_mfma_f32_16x16x32_bf16 v[74:77], v[154:157], v[210:213], v[74:77]
	v_mfma_f32_16x16x32_bf16 v[126:129], v[150:153], v[182:185], v[126:129]
	v_mfma_f32_16x16x32_bf16 v[122:125], v[158:161], v[182:185], v[122:125]
	v_mfma_f32_16x16x32_bf16 v[110:113], v[150:153], v[198:201], v[110:113]
	v_mfma_f32_16x16x32_bf16 v[106:109], v[158:161], v[198:201], v[106:109]
	v_mfma_f32_16x16x32_bf16 v[94:97], v[150:153], v[206:209], v[94:97]
	v_mfma_f32_16x16x32_bf16 v[90:93], v[158:161], v[206:209], v[90:93]
	v_mfma_f32_16x16x32_bf16 v[78:81], v[150:153], v[216:219], v[78:81]
	v_mfma_f32_16x16x32_bf16 v[74:77], v[158:161], v[216:219], v[74:77]
	v_mfma_f32_16x16x32_bf16 v[118:121], v[162:165], v[178:181], v[118:121]
	v_mfma_f32_16x16x32_bf16 v[114:117], v[170:173], v[178:181], v[114:117]
	v_mfma_f32_16x16x32_bf16 v[102:105], v[162:165], v[186:189], v[102:105]
	v_mfma_f32_16x16x32_bf16 v[98:101], v[170:173], v[186:189], v[98:101]
	v_mfma_f32_16x16x32_bf16 v[86:89], v[162:165], v[202:205], v[86:89]
	v_mfma_f32_16x16x32_bf16 v[82:85], v[170:173], v[202:205], v[82:85]
	v_mfma_f32_16x16x32_bf16 v[70:73], v[162:165], v[210:213], v[70:73]
	v_mfma_f32_16x16x32_bf16 v[66:69], v[170:173], v[210:213], v[66:69]
	v_mfma_f32_16x16x32_bf16 v[118:121], v[166:169], v[182:185], v[118:121]
	v_mfma_f32_16x16x32_bf16 v[114:117], v[174:177], v[182:185], v[114:117]
	v_mfma_f32_16x16x32_bf16 v[102:105], v[166:169], v[198:201], v[102:105]
	v_mfma_f32_16x16x32_bf16 v[98:101], v[174:177], v[198:201], v[98:101]
	v_mfma_f32_16x16x32_bf16 v[86:89], v[166:169], v[206:209], v[86:89]
	v_mfma_f32_16x16x32_bf16 v[82:85], v[174:177], v[206:209], v[82:85]
	v_mfma_f32_16x16x32_bf16 v[70:73], v[166:169], v[216:219], v[70:73]
	v_mfma_f32_16x16x32_bf16 v[66:69], v[174:177], v[216:219], v[66:69]
	s_barrier
	s_add_i32 s22, s60, s30
	v_lshl_add_u64 v[190:191], v[190:191], 0, s[18:19]
	s_mov_b32 m0, s22
	ds_read_b128 v[178:181], v196 offset:49152
	ds_read_b128 v[182:185], v196 offset:50176
	ds_read_b128 v[186:189], v196 offset:51200
	ds_read_b128 v[198:201], v196 offset:52224
	ds_read_b128 v[202:205], v196 offset:53248
	ds_read_b128 v[206:209], v196 offset:54272
	ds_read_b128 v[210:213], v196 offset:55296
	ds_read_b128 v[216:219], v196 offset:56320
	global_load_lds_dwordx4 v[190:191], off
	s_add_i32 m0, s22, 0x2000
	s_add_u32 s22, s26, 0x2b0080
	v_lshl_add_u64 v[190:191], v[220:221], 0, s[18:19]
	s_addc_u32 s23, s27, 0
	s_add_i32 s26, s61, s30
	global_load_lds_dwordx4 v[190:191], off
	v_lshl_add_u64 v[190:191], s[22:23], 0, v[140:141]
	s_mov_b32 m0, s26
	s_nop 0
	global_load_lds_dwordx4 v[190:191], off
	v_lshl_add_u64 v[190:191], s[22:23], 0, v[136:137]
	s_add_i32 m0, s26, 0x2000
	s_nop 0
	global_load_lds_dwordx4 v[190:191], off
	v_lshl_add_u64 v[190:191], v[222:223], 0, s[18:19]
	s_mov_b32 m0, s52
	s_nop 0
	global_load_lds_dwordx4 v[190:191], off
	v_lshl_add_u64 v[190:191], v[224:225], 0, s[18:19]
	s_mov_b32 m0, s53
	s_nop 0
	global_load_lds_dwordx4 v[190:191], off
	s_waitcnt vmcnt(8)
	s_waitcnt lgkmcnt(0)
	s_barrier
	s_waitcnt lgkmcnt(0)
	v_mfma_f32_16x16x32_bf16 v[62:65], v[132:135], v[178:181], v[62:65]
	v_mfma_f32_16x16x32_bf16 v[58:61], v[154:157], v[178:181], v[58:61]
	v_mfma_f32_16x16x32_bf16 v[46:49], v[132:135], v[186:189], v[46:49]
	v_mfma_f32_16x16x32_bf16 v[42:45], v[154:157], v[186:189], v[42:45]
	v_mfma_f32_16x16x32_bf16 v[30:33], v[132:135], v[202:205], v[30:33]
	v_mfma_f32_16x16x32_bf16 v[26:29], v[154:157], v[202:205], v[26:29]
	v_mfma_f32_16x16x32_bf16 v[14:17], v[132:135], v[210:213], v[14:17]
	v_mfma_f32_16x16x32_bf16 v[10:13], v[154:157], v[210:213], v[10:13]
	s_add_i32 s59, s59, 2
	v_mfma_f32_16x16x32_bf16 v[62:65], v[150:153], v[182:185], v[62:65]
	s_add_u32 s57, s57, 0x100
	v_mfma_f32_16x16x32_bf16 v[58:61], v[158:161], v[182:185], v[58:61]
	s_addc_u32 s58, s58, 0
	v_mfma_f32_16x16x32_bf16 v[46:49], v[150:153], v[198:201], v[46:49]
	s_cmpk_gt_u32 s59, 0xa9
	v_mfma_f32_16x16x32_bf16 v[42:45], v[158:161], v[198:201], v[42:45]
	s_mov_b64 s[22:23], s[24:25]
	v_mfma_f32_16x16x32_bf16 v[30:33], v[150:153], v[206:209], v[30:33]
	v_mfma_f32_16x16x32_bf16 v[26:29], v[158:161], v[206:209], v[26:29]
	v_mfma_f32_16x16x32_bf16 v[14:17], v[150:153], v[216:219], v[14:17]
	v_mfma_f32_16x16x32_bf16 v[10:13], v[158:161], v[216:219], v[10:13]
	v_mfma_f32_16x16x32_bf16 v[54:57], v[162:165], v[178:181], v[54:57]
	v_mfma_f32_16x16x32_bf16 v[50:53], v[170:173], v[178:181], v[50:53]
	v_mfma_f32_16x16x32_bf16 v[38:41], v[162:165], v[186:189], v[38:41]
	v_mfma_f32_16x16x32_bf16 v[34:37], v[170:173], v[186:189], v[34:37]
	v_mfma_f32_16x16x32_bf16 v[22:25], v[162:165], v[202:205], v[22:25]
	v_mfma_f32_16x16x32_bf16 v[18:21], v[170:173], v[202:205], v[18:21]
	v_mfma_f32_16x16x32_bf16 v[6:9], v[162:165], v[210:213], v[6:9]
	v_mfma_f32_16x16x32_bf16 v[2:5], v[170:173], v[210:213], v[2:5]
	v_mfma_f32_16x16x32_bf16 v[54:57], v[166:169], v[182:185], v[54:57]
	v_mfma_f32_16x16x32_bf16 v[50:53], v[174:177], v[182:185], v[50:53]
	v_mfma_f32_16x16x32_bf16 v[38:41], v[166:169], v[198:201], v[38:41]
	v_mfma_f32_16x16x32_bf16 v[34:37], v[174:177], v[198:201], v[34:37]
	v_mfma_f32_16x16x32_bf16 v[22:25], v[166:169], v[206:209], v[22:25]
	v_mfma_f32_16x16x32_bf16 v[18:21], v[174:177], v[206:209], v[18:21]
	v_mfma_f32_16x16x32_bf16 v[6:9], v[166:169], v[216:219], v[6:9]
	v_mfma_f32_16x16x32_bf16 v[2:5], v[174:177], v[216:219], v[2:5]
	s_barrier
	s_cbranch_scc0 .LBB0_1354
	s_and_b64 vcc, exec, s[46:47]
	s_cbranch_vccz .LBB0_1357
	s_barrier

.LBB0_1405:
	s_add_u32 s22, s16, 0x100
	s_addc_u32 s23, s17, 0
	s_add_i32 s54, 0, 0x10000
	s_cmpk_eq_i32 s53, 0xa8
	s_cselect_b32 s27, s3, s23
	s_cselect_b32 s26, s2, s22
	v_add_u32_e32 v148, s54, v152
	s_cselect_b32 s25, s13, s52
	s_cselect_b32 s24, s12, s51
	s_add_i32 s55, 0, 0x14000
	ds_read_b128 v[144:147], v148
	ds_read_b128 v[156:159], v148 offset:1024
	ds_read_b128 v[160:163], v148 offset:2048
	ds_read_b128 v[164:167], v148 offset:3072
	v_add_u32_e32 v148, s55, v152
	ds_read_b128 v[168:171], v148
	ds_read_b128 v[172:175], v148 offset:1024
	ds_read_b128 v[176:179], v148 offset:2048
	ds_read_b128 v[180:183], v148 offset:3072
	v_lshl_add_u64 v[148:149], s[16:17], 0, v[140:141]
	s_add_i32 m0, s29, 0xc000
	ds_read_b128 v[184:187], v154
	ds_read_b128 v[188:191], v154 offset:1024
	ds_read_b128 v[192:195], v154 offset:2048
	ds_read_b128 v[196:199], v154 offset:3072
	ds_read_b128 v[200:203], v154 offset:4096
	ds_read_b128 v[204:207], v154 offset:5120
	ds_read_b128 v[208:211], v154 offset:6144
	ds_read_b128 v[216:219], v154 offset:7168
	global_load_lds_dwordx4 v[148:149], off
	v_lshl_add_u64 v[148:149], s[16:17], 0, v[142:143]
	s_add_i32 m0, s29, 0xe000
	s_nop 0
	global_load_lds_dwordx4 v[148:149], off
	s_waitcnt vmcnt(8)
	s_waitcnt lgkmcnt(0)
	s_barrier
	s_waitcnt lgkmcnt(0)
	v_mfma_f32_16x16x32_bf16 v[126:129], v[144:147], v[184:187], v[126:129]
	v_mfma_f32_16x16x32_bf16 v[122:125], v[160:163], v[184:187], v[122:125]
	v_mfma_f32_16x16x32_bf16 v[110:113], v[144:147], v[192:195], v[110:113]
	v_mfma_f32_16x16x32_bf16 v[106:109], v[160:163], v[192:195], v[106:109]
	v_mfma_f32_16x16x32_bf16 v[94:97], v[144:147], v[200:203], v[94:97]
	v_mfma_f32_16x16x32_bf16 v[90:93], v[160:163], v[200:203], v[90:93]
	v_mfma_f32_16x16x32_bf16 v[78:81], v[144:147], v[208:211], v[78:81]
	v_mfma_f32_16x16x32_bf16 v[74:77], v[160:163], v[208:211], v[74:77]
	v_mfma_f32_16x16x32_bf16 v[126:129], v[156:159], v[188:191], v[126:129]
	v_mfma_f32_16x16x32_bf16 v[122:125], v[164:167], v[188:191], v[122:125]
	v_mfma_f32_16x16x32_bf16 v[110:113], v[156:159], v[196:199], v[110:113]
	v_mfma_f32_16x16x32_bf16 v[106:109], v[164:167], v[196:199], v[106:109]
	v_mfma_f32_16x16x32_bf16 v[94:97], v[156:159], v[204:207], v[94:97]
	v_mfma_f32_16x16x32_bf16 v[90:93], v[164:167], v[204:207], v[90:93]
	v_mfma_f32_16x16x32_bf16 v[78:81], v[156:159], v[216:219], v[78:81]
	v_mfma_f32_16x16x32_bf16 v[74:77], v[164:167], v[216:219], v[74:77]
	v_mfma_f32_16x16x32_bf16 v[118:121], v[168:171], v[184:187], v[118:121]
	v_mfma_f32_16x16x32_bf16 v[114:117], v[176:179], v[184:187], v[114:117]
	v_mfma_f32_16x16x32_bf16 v[102:105], v[168:171], v[192:195], v[102:105]
	v_mfma_f32_16x16x32_bf16 v[98:101], v[176:179], v[192:195], v[98:101]
	v_mfma_f32_16x16x32_bf16 v[86:89], v[168:171], v[200:203], v[86:89]
	v_mfma_f32_16x16x32_bf16 v[82:85], v[176:179], v[200:203], v[82:85]
	v_mfma_f32_16x16x32_bf16 v[70:73], v[168:171], v[208:211], v[70:73]
	v_mfma_f32_16x16x32_bf16 v[66:69], v[176:179], v[208:211], v[66:69]
	v_mfma_f32_16x16x32_bf16 v[118:121], v[172:175], v[188:191], v[118:121]
	v_mfma_f32_16x16x32_bf16 v[114:117], v[180:183], v[188:191], v[114:117]
	v_mfma_f32_16x16x32_bf16 v[102:105], v[172:175], v[196:199], v[102:105]
	v_mfma_f32_16x16x32_bf16 v[98:101], v[180:183], v[196:199], v[98:101]
	v_mfma_f32_16x16x32_bf16 v[86:89], v[172:175], v[204:207], v[86:89]
	v_mfma_f32_16x16x32_bf16 v[82:85], v[180:183], v[204:207], v[82:85]
	v_mfma_f32_16x16x32_bf16 v[70:73], v[172:175], v[216:219], v[70:73]
	v_mfma_f32_16x16x32_bf16 v[66:69], v[180:183], v[216:219], v[66:69]
	s_barrier
	s_add_i32 s16, s54, s28
	v_lshl_add_u64 v[148:149], s[24:25], 0, v[130:131]
	s_mov_b32 m0, s16
	ds_read_b128 v[184:187], v154 offset:16384
	ds_read_b128 v[188:191], v154 offset:17408
	ds_read_b128 v[192:195], v154 offset:18432
	ds_read_b128 v[196:199], v154 offset:19456
	ds_read_b128 v[200:203], v154 offset:20480
	ds_read_b128 v[204:207], v154 offset:21504
	ds_read_b128 v[208:211], v154 offset:22528
	ds_read_b128 v[216:219], v154 offset:23552
	global_load_lds_dwordx4 v[148:149], off
	s_add_i32 m0, s16, 0x2000
	s_add_u32 s16, s24, 0x2b0000
	v_lshl_add_u64 v[212:213], s[24:25], 0, v[132:133]
	s_addc_u32 s17, s25, 0
	s_add_i32 s54, s55, s28
	global_load_lds_dwordx4 v[212:213], off
	v_lshl_add_u64 v[220:221], s[16:17], 0, v[130:131]
	s_mov_b32 m0, s54
	v_lshl_add_u64 v[222:223], s[26:27], 0, v[134:135]
	global_load_lds_dwordx4 v[220:221], off
	v_lshl_add_u64 v[220:221], s[16:17], 0, v[132:133]
	s_add_i32 m0, s54, 0x2000
	s_nop 0
	global_load_lds_dwordx4 v[220:221], off
	v_lshl_add_u64 v[220:221], s[26:27], 0, v[136:137]
	s_mov_b32 m0, s29
	s_nop 0
	global_load_lds_dwordx4 v[220:221], off
	s_mov_b32 m0, s30
	s_nop 0
	global_load_lds_dwordx4 v[222:223], off
	s_waitcnt vmcnt(8)
	s_waitcnt lgkmcnt(0)
	s_barrier
	s_waitcnt lgkmcnt(0)
	v_mfma_f32_16x16x32_bf16 v[62:65], v[144:147], v[184:187], v[62:65]
	v_mfma_f32_16x16x32_bf16 v[58:61], v[160:163], v[184:187], v[58:61]
	v_mfma_f32_16x16x32_bf16 v[46:49], v[144:147], v[192:195], v[46:49]
	v_mfma_f32_16x16x32_bf16 v[42:45], v[160:163], v[192:195], v[42:45]
	v_mfma_f32_16x16x32_bf16 v[30:33], v[144:147], v[200:203], v[30:33]
	v_mfma_f32_16x16x32_bf16 v[26:29], v[160:163], v[200:203], v[26:29]
	v_mfma_f32_16x16x32_bf16 v[14:17], v[144:147], v[208:211], v[14:17]
	v_mfma_f32_16x16x32_bf16 v[10:13], v[160:163], v[208:211], v[10:13]
	v_mfma_f32_16x16x32_bf16 v[62:65], v[156:159], v[188:191], v[62:65]
	v_mfma_f32_16x16x32_bf16 v[58:61], v[164:167], v[188:191], v[58:61]
	v_mfma_f32_16x16x32_bf16 v[46:49], v[156:159], v[196:199], v[46:49]
	v_mfma_f32_16x16x32_bf16 v[42:45], v[164:167], v[196:199], v[42:45]
	v_mfma_f32_16x16x32_bf16 v[30:33], v[156:159], v[204:207], v[30:33]
	v_mfma_f32_16x16x32_bf16 v[26:29], v[164:167], v[204:207], v[26:29]
	v_mfma_f32_16x16x32_bf16 v[14:17], v[156:159], v[216:219], v[14:17]
	v_mfma_f32_16x16x32_bf16 v[10:13], v[164:167], v[216:219], v[10:13]
	v_mfma_f32_16x16x32_bf16 v[54:57], v[168:171], v[184:187], v[54:57]
	v_mfma_f32_16x16x32_bf16 v[50:53], v[176:179], v[184:187], v[50:53]
	v_mfma_f32_16x16x32_bf16 v[38:41], v[168:171], v[192:195], v[38:41]
	v_mfma_f32_16x16x32_bf16 v[34:37], v[176:179], v[192:195], v[34:37]
	v_mfma_f32_16x16x32_bf16 v[22:25], v[168:171], v[200:203], v[22:25]
	v_mfma_f32_16x16x32_bf16 v[18:21], v[176:179], v[200:203], v[18:21]
	v_mfma_f32_16x16x32_bf16 v[6:9], v[168:171], v[208:211], v[6:9]
	v_mfma_f32_16x16x32_bf16 v[2:5], v[176:179], v[208:211], v[2:5]
	v_mfma_f32_16x16x32_bf16 v[54:57], v[172:175], v[188:191], v[54:57]
	v_mfma_f32_16x16x32_bf16 v[50:53], v[180:183], v[188:191], v[50:53]
	v_mfma_f32_16x16x32_bf16 v[38:41], v[172:175], v[196:199], v[38:41]
	v_mfma_f32_16x16x32_bf16 v[34:37], v[180:183], v[196:199], v[34:37]
	v_mfma_f32_16x16x32_bf16 v[22:25], v[172:175], v[204:207], v[22:25]
	v_mfma_f32_16x16x32_bf16 v[18:21], v[180:183], v[204:207], v[18:21]
	v_mfma_f32_16x16x32_bf16 v[6:9], v[172:175], v[216:219], v[6:9]
	v_mfma_f32_16x16x32_bf16 v[2:5], v[180:183], v[216:219], v[2:5]
	s_barrier
	s_add_i32 s54, 0, 0x18000
	v_add_u32_e32 v155, s54, v152
	s_add_i32 s55, 0, 0x1c000
	ds_read_b128 v[144:147], v155
	ds_read_b128 v[156:159], v155 offset:1024
	ds_read_b128 v[160:163], v155 offset:2048
	ds_read_b128 v[164:167], v155 offset:3072
	v_add_u32_e32 v155, s55, v152
	ds_read_b128 v[168:171], v155
	ds_read_b128 v[172:175], v155 offset:1024
	ds_read_b128 v[176:179], v155 offset:2048
	ds_read_b128 v[180:183], v155 offset:3072
	s_add_u32 s16, s26, 0x2b0000
	s_addc_u32 s17, s27, 0
	s_mov_b32 m0, s40
	v_lshl_add_u64 v[224:225], s[16:17], 0, v[136:137]
	ds_read_b128 v[184:187], v154 offset:32768
	ds_read_b128 v[188:191], v154 offset:33792
	ds_read_b128 v[192:195], v154 offset:34816
	ds_read_b128 v[196:199], v154 offset:35840
	ds_read_b128 v[200:203], v154 offset:36864
	ds_read_b128 v[204:207], v154 offset:37888
	ds_read_b128 v[208:211], v154 offset:38912
	ds_read_b128 v[216:219], v154 offset:39936
	global_load_lds_dwordx4 v[224:225], off
	v_lshl_add_u64 v[224:225], s[16:17], 0, v[134:135]
	s_mov_b32 m0, s41
	s_nop 0
	global_load_lds_dwordx4 v[224:225], off
	s_waitcnt vmcnt(8)
	s_waitcnt lgkmcnt(0)
	s_barrier
	s_waitcnt lgkmcnt(0)
	v_mfma_f32_16x16x32_bf16 v[126:129], v[144:147], v[184:187], v[126:129]
	v_mfma_f32_16x16x32_bf16 v[122:125], v[160:163], v[184:187], v[122:125]
	v_mfma_f32_16x16x32_bf16 v[110:113], v[144:147], v[192:195], v[110:113]
	v_mfma_f32_16x16x32_bf16 v[106:109], v[160:163], v[192:195], v[106:109]
	v_mfma_f32_16x16x32_bf16 v[94:97], v[144:147], v[200:203], v[94:97]
	v_mfma_f32_16x16x32_bf16 v[90:93], v[160:163], v[200:203], v[90:93]
	v_mfma_f32_16x16x32_bf16 v[78:81], v[144:147], v[208:211], v[78:81]
	v_mfma_f32_16x16x32_bf16 v[74:77], v[160:163], v[208:211], v[74:77]
	v_mfma_f32_16x16x32_bf16 v[126:129], v[156:159], v[188:191], v[126:129]
	v_mfma_f32_16x16x32_bf16 v[122:125], v[164:167], v[188:191], v[122:125]
	v_mfma_f32_16x16x32_bf16 v[110:113], v[156:159], v[196:199], v[110:113]
	v_mfma_f32_16x16x32_bf16 v[106:109], v[164:167], v[196:199], v[106:109]
	v_mfma_f32_16x16x32_bf16 v[94:97], v[156:159], v[204:207], v[94:97]
	v_mfma_f32_16x16x32_bf16 v[90:93], v[164:167], v[204:207], v[90:93]
	v_mfma_f32_16x16x32_bf16 v[78:81], v[156:159], v[216:219], v[78:81]
	v_mfma_f32_16x16x32_bf16 v[74:77], v[164:167], v[216:219], v[74:77]
	v_mfma_f32_16x16x32_bf16 v[118:121], v[168:171], v[184:187], v[118:121]
	v_mfma_f32_16x16x32_bf16 v[114:117], v[176:179], v[184:187], v[114:117]
	v_mfma_f32_16x16x32_bf16 v[102:105], v[168:171], v[192:195], v[102:105]
	v_mfma_f32_16x16x32_bf16 v[98:101], v[176:179], v[192:195], v[98:101]
	v_mfma_f32_16x16x32_bf16 v[86:89], v[168:171], v[200:203], v[86:89]
	v_mfma_f32_16x16x32_bf16 v[82:85], v[176:179], v[200:203], v[82:85]
	v_mfma_f32_16x16x32_bf16 v[70:73], v[168:171], v[208:211], v[70:73]
	v_mfma_f32_16x16x32_bf16 v[66:69], v[176:179], v[208:211], v[66:69]
	v_mfma_f32_16x16x32_bf16 v[118:121], v[172:175], v[188:191], v[118:121]
	v_mfma_f32_16x16x32_bf16 v[114:117], v[180:183], v[188:191], v[114:117]
	v_mfma_f32_16x16x32_bf16 v[102:105], v[172:175], v[196:199], v[102:105]
	v_mfma_f32_16x16x32_bf16 v[98:101], v[180:183], v[196:199], v[98:101]
	v_mfma_f32_16x16x32_bf16 v[86:89], v[172:175], v[204:207], v[86:89]
	v_mfma_f32_16x16x32_bf16 v[82:85], v[180:183], v[204:207], v[82:85]
	v_mfma_f32_16x16x32_bf16 v[70:73], v[172:175], v[216:219], v[70:73]
	v_mfma_f32_16x16x32_bf16 v[66:69], v[180:183], v[216:219], v[66:69]
	s_barrier
	s_add_i32 s16, s54, s28
	v_lshl_add_u64 v[148:149], v[148:149], 0, s[18:19]
	s_mov_b32 m0, s16
	ds_read_b128 v[184:187], v154 offset:49152
	ds_read_b128 v[188:191], v154 offset:50176
	ds_read_b128 v[192:195], v154 offset:51200
	ds_read_b128 v[196:199], v154 offset:52224
	ds_read_b128 v[200:203], v154 offset:53248
	ds_read_b128 v[204:207], v154 offset:54272
	ds_read_b128 v[208:211], v154 offset:55296
	ds_read_b128 v[216:219], v154 offset:56320
	global_load_lds_dwordx4 v[148:149], off
	s_add_i32 m0, s16, 0x2000
	s_add_u32 s16, s24, 0x2b0080
	v_lshl_add_u64 v[148:149], v[212:213], 0, s[18:19]
	s_addc_u32 s17, s25, 0
	s_add_i32 s24, s55, s28
	global_load_lds_dwordx4 v[148:149], off
	v_lshl_add_u64 v[148:149], s[16:17], 0, v[130:131]
	s_mov_b32 m0, s24
	s_nop 0
	global_load_lds_dwordx4 v[148:149], off
	v_lshl_add_u64 v[148:149], s[16:17], 0, v[132:133]
	s_add_i32 m0, s24, 0x2000
	s_nop 0
	global_load_lds_dwordx4 v[148:149], off
	v_lshl_add_u64 v[148:149], v[220:221], 0, s[18:19]
	s_mov_b32 m0, s44
	s_nop 0
	global_load_lds_dwordx4 v[148:149], off
	v_lshl_add_u64 v[148:149], v[222:223], 0, s[18:19]
	s_mov_b32 m0, s45
	s_nop 0
	global_load_lds_dwordx4 v[148:149], off
	s_waitcnt vmcnt(8)
	s_waitcnt lgkmcnt(0)
	s_barrier
	s_waitcnt lgkmcnt(0)
	v_mfma_f32_16x16x32_bf16 v[62:65], v[144:147], v[184:187], v[62:65]
	v_mfma_f32_16x16x32_bf16 v[58:61], v[160:163], v[184:187], v[58:61]
	v_mfma_f32_16x16x32_bf16 v[46:49], v[144:147], v[192:195], v[46:49]
	v_mfma_f32_16x16x32_bf16 v[42:45], v[160:163], v[192:195], v[42:45]
	v_mfma_f32_16x16x32_bf16 v[30:33], v[144:147], v[200:203], v[30:33]
	v_mfma_f32_16x16x32_bf16 v[26:29], v[160:163], v[200:203], v[26:29]
	v_mfma_f32_16x16x32_bf16 v[14:17], v[144:147], v[208:211], v[14:17]
	v_mfma_f32_16x16x32_bf16 v[10:13], v[160:163], v[208:211], v[10:13]
	s_add_i32 s53, s53, 2
	v_mfma_f32_16x16x32_bf16 v[62:65], v[156:159], v[188:191], v[62:65]
	s_add_u32 s51, s51, 0x100
	v_mfma_f32_16x16x32_bf16 v[58:61], v[164:167], v[188:191], v[58:61]
	s_addc_u32 s52, s52, 0
	v_mfma_f32_16x16x32_bf16 v[46:49], v[156:159], v[196:199], v[46:49]
	s_cmpk_gt_u32 s53, 0xa9
	v_mfma_f32_16x16x32_bf16 v[42:45], v[164:167], v[196:199], v[42:45]
	s_mov_b64 s[16:17], s[22:23]
	v_mfma_f32_16x16x32_bf16 v[30:33], v[156:159], v[204:207], v[30:33]
	v_mfma_f32_16x16x32_bf16 v[26:29], v[164:167], v[204:207], v[26:29]
	v_mfma_f32_16x16x32_bf16 v[14:17], v[156:159], v[216:219], v[14:17]
	v_mfma_f32_16x16x32_bf16 v[10:13], v[164:167], v[216:219], v[10:13]
	v_mfma_f32_16x16x32_bf16 v[54:57], v[168:171], v[184:187], v[54:57]
	v_mfma_f32_16x16x32_bf16 v[50:53], v[176:179], v[184:187], v[50:53]
	v_mfma_f32_16x16x32_bf16 v[38:41], v[168:171], v[192:195], v[38:41]
	v_mfma_f32_16x16x32_bf16 v[34:37], v[176:179], v[192:195], v[34:37]
	v_mfma_f32_16x16x32_bf16 v[22:25], v[168:171], v[200:203], v[22:25]
	v_mfma_f32_16x16x32_bf16 v[18:21], v[176:179], v[200:203], v[18:21]
	v_mfma_f32_16x16x32_bf16 v[6:9], v[168:171], v[208:211], v[6:9]
	v_mfma_f32_16x16x32_bf16 v[2:5], v[176:179], v[208:211], v[2:5]
	v_mfma_f32_16x16x32_bf16 v[54:57], v[172:175], v[188:191], v[54:57]
	v_mfma_f32_16x16x32_bf16 v[50:53], v[180:183], v[188:191], v[50:53]
	v_mfma_f32_16x16x32_bf16 v[38:41], v[172:175], v[196:199], v[38:41]
	v_mfma_f32_16x16x32_bf16 v[34:37], v[180:183], v[196:199], v[34:37]
	v_mfma_f32_16x16x32_bf16 v[22:25], v[172:175], v[204:207], v[22:25]
	v_mfma_f32_16x16x32_bf16 v[18:21], v[180:183], v[204:207], v[18:21]
	v_mfma_f32_16x16x32_bf16 v[6:9], v[172:175], v[216:219], v[6:9]
	v_mfma_f32_16x16x32_bf16 v[2:5], v[180:183], v[216:219], v[2:5]
	s_barrier
	s_cbranch_scc0 .LBB0_1405
	s_and_b64 vcc, exec, s[6:7]
	s_cbranch_vccz .LBB0_1408
	s_barrier
